# adds: fftA MFMA section rebuilt with a 6-deep LDS read ring and the next unit's 8 loads issued one per 4 steps inside it; fftB likewise with gate prefetch and next loads spread over the staging code
# speedup vs baseline: 1.0389x; 1.0068x over previous
.LBB0_329:
	s_or_b64 exec, exec, s[0:1]
	v_readlane_b32 s0, v253, 47
	v_readlane_b32 s1, v253, 48
	s_and_b64 vcc, exec, s[0:1]
	s_cbranch_vccz .LBB0_343
	v_ashrrev_i32_e32 v123, 3, v122
	v_readlane_b32 s0, v254, 22
	v_lshlrev_b32_e32 v1, 4, v122
	v_and_b32_e32 v208, 0x70, v1
	v_lshlrev_b32_e32 v0, s0, v123
	v_readlane_b32 s0, v254, 20
	v_and_b32_e32 v32, 24, v32
	v_and_b32_e32 v35, 15, v122
	v_add_u32_e32 v0, s0, v0
	v_or_b32_e32 v2, 3, v0
	v_ashrrev_i32_e32 v3, 31, v2
	v_readlane_b32 s0, v254, 33
	v_lshlrev_b64 v[2:3], 11, v[2:3]
	v_readlane_b32 s1, v254, 34
	v_ashrrev_i32_e32 v1, 31, v0
	v_bfe_u32 v33, v122, 4, 2
	v_lshl_add_u64 v[2:3], s[0:1], 0, v[2:3]
	v_lshl_add_u64 v[2:3], v[2:3], 0, v[208:209]
	global_load_dwordx4 v[24:27], v[2:3], off offset:1024
	global_load_dwordx4 v[28:31], v[2:3], off
	v_or_b32_e32 v2, 2, v0
	v_ashrrev_i32_e32 v3, 31, v2
	v_lshlrev_b64 v[2:3], 11, v[2:3]
	v_lshl_add_u64 v[2:3], s[0:1], 0, v[2:3]
	v_lshl_add_u64 v[2:3], v[2:3], 0, v[208:209]
	global_load_dwordx4 v[16:19], v[2:3], off offset:1024
	global_load_dwordx4 v[20:23], v[2:3], off
	v_or_b32_e32 v2, 1, v0
	v_ashrrev_i32_e32 v3, 31, v2
	v_lshlrev_b64 v[2:3], 11, v[2:3]
	v_lshlrev_b64 v[0:1], 11, v[0:1]
	v_lshl_add_u64 v[2:3], s[0:1], 0, v[2:3]
	v_lshl_add_u64 v[0:1], s[0:1], 0, v[0:1]
	v_lshl_add_u64 v[2:3], v[2:3], 0, v[208:209]
	v_lshl_add_u64 v[4:5], v[0:1], 0, v[208:209]
	global_load_dwordx4 v[8:11], v[2:3], off offset:1024
	global_load_dwordx4 v[12:15], v[2:3], off
	s_nop 0
	global_load_dwordx4 v[0:3], v[4:5], off offset:1024
	s_nop 0
	global_load_dwordx4 v[4:7], v[4:5], off
	s_and_b32 s0, s15, 0xffffffc0
	s_add_i32 s0, s0, 0
	v_add_u32_e32 v37, s0, v32
	s_and_b32 s0, s15, 64
	v_bfe_u32 v36, v122, 2, 2
	s_add_i32 s0, s0, 0
	v_bfe_u32 v32, v122, 3, 1
	v_lshl_or_b32 v36, v33, 3, v36
	v_lshlrev_b32_e32 v125, 2, v33
	v_lshl_add_u32 v39, v33, 4, 0
	v_lshl_add_u32 v40, v35, 1, s0
	v_lshlrev_b32_e32 v33, 7, v32
	v_readlane_b32 s0, v254, 31
	v_add3_u32 v41, 0, v33, v208
	v_lshlrev_b32_e32 v32, 10, v32
	v_mov_b32_e32 v33, v209
	v_readlane_b32 s1, v254, 32
	v_mov_b32_e32 v42, 0x8400
	v_mov_b32_e32 v43, 0xc600
	v_lshl_add_u64 v[32:33], s[0:1], 0, v[32:33]
	s_movk_i32 s0, 0x210
	v_lshl_add_u64 v[120:121], v[32:33], 0, v[208:209]
	v_mul_lo_u32 v32, v123, s0
	v_mul_u32_u24_e32 v33, 0x210, v36
	v_mad_u32_u24 v42, v36, s0, v42
	v_mad_u32_u24 v36, v36, s0, v43
	s_movk_i32 s0, 0x110
	v_add_u32_e32 v44, 0x200, v122
	v_add_u32_e32 v45, 0x400, v122
	v_ashrrev_i32_e32 v61, 4, v122
	v_add_u32_e32 v46, 0x600, v122
	v_mul_lo_u32 v62, v61, s0
	v_and_b32_e32 v128, 63, v61
	v_ashrrev_i32_e32 v61, 4, v44
	v_ashrrev_i32_e32 v129, 10, v44
	v_ashrrev_i32_e32 v44, 4, v45
	v_mul_lo_u32 v63, v61, s0
	v_and_b32_e32 v130, 63, v61
	v_mul_lo_u32 v61, v44, s0
	v_and_b32_e32 v132, 63, v44
	v_ashrrev_i32_e32 v44, 4, v46
	v_ashrrev_i32_e32 v131, 10, v45
	v_mul_lo_u32 v45, v44, s0
	v_and_b32_e32 v134, 63, v44
	v_add_u32_e32 v44, 0x800, v122
	v_ashrrev_i32_e32 v133, 10, v46
	v_ashrrev_i32_e32 v46, 4, v44
	v_ashrrev_i32_e32 v135, 10, v44
	v_add_u32_e32 v44, 0xa00, v122
	s_ashr_i32 s2, s15, 7
	v_mul_lo_u32 v64, v46, s0
	v_and_b32_e32 v136, 63, v46
	v_ashrrev_i32_e32 v46, 4, v44
	v_ashrrev_i32_e32 v137, 10, v44
	v_add_u32_e32 v44, 0xc00, v122
	v_lshl_or_b32 v38, s2, 6, v125
	v_mul_lo_u32 v65, v46, s0
	v_and_b32_e32 v138, 63, v46
	v_ashrrev_i32_e32 v46, 4, v44
	v_ashrrev_i32_e32 v139, 10, v44
	v_add_u32_e32 v44, 0xe00, v122
	v_and_b32_e32 v34, 7, v122
	v_add_u32_e32 v126, 0, v32
	v_mul_lo_u32 v43, v38, s0
	v_or_b32_e32 v47, 1, v38
	v_or_b32_e32 v48, 2, v38
	v_or_b32_e32 v49, 3, v38
	v_or_b32_e32 v50, 16, v38
	v_or_b32_e32 v51, 17, v38
	v_or_b32_e32 v52, 18, v38
	v_or_b32_e32 v53, 19, v38
	v_or_b32_e32 v54, 32, v38
	v_or_b32_e32 v55, 33, v38
	v_or_b32_e32 v56, 34, v38
	v_or_b32_e32 v57, 35, v38
	v_or_b32_e32 v58, 48, v38
	v_or_b32_e32 v59, 49, v38
	v_or_b32_e32 v60, 50, v38
	v_or_b32_e32 v38, 51, v38
	v_mul_lo_u32 v66, v46, s0
	v_and_b32_e32 v140, 63, v46
	v_ashrrev_i32_e32 v46, 4, v44
	v_lshlrev_b32_e32 v124, 4, v34
	v_lshlrev_b32_e32 v34, 3, v34
	v_add_u32_e32 v32, 0x8800, v126
	v_mul_u32_u24_e32 v35, 0x110, v35
	v_mul_lo_u32 v47, v47, s0
	v_mul_lo_u32 v48, v48, s0
	v_mul_lo_u32 v49, v49, s0
	v_mul_lo_u32 v50, v50, s0
	v_mul_lo_u32 v51, v51, s0
	v_mul_lo_u32 v52, v52, s0
	v_mul_lo_u32 v53, v53, s0
	v_mul_lo_u32 v54, v54, s0
	v_mul_lo_u32 v55, v55, s0
	v_mul_lo_u32 v56, v56, s0
	v_mul_lo_u32 v57, v57, s0
	v_mul_lo_u32 v58, v58, s0
	v_mul_lo_u32 v59, v59, s0
	v_mul_lo_u32 v60, v60, s0
	v_mul_lo_u32 v38, v38, s0
	v_mul_lo_u32 v67, v46, s0
	v_ashrrev_i32_e32 v127, 10, v122
	v_ashrrev_i32_e32 v141, 10, v44
	v_and_b32_e32 v142, 63, v46
	s_mov_b32 s10, 0
	v_add_u32_e32 v143, v32, v124
	v_lshlrev_b32_e32 v208, 1, v34
	v_add_u32_e32 v144, v37, v33
	v_add_u32_e32 v145, v37, v42
	v_add_u32_e32 v146, v37, v36
	v_add_u32_e32 v147, v39, v35
	v_add_u32_e32 v148, v40, v43
	v_add_u32_e32 v149, v40, v47
	v_add_u32_e32 v150, v40, v48
	v_add_u32_e32 v151, v40, v49
	v_add_u32_e32 v152, v40, v50
	v_add_u32_e32 v153, v40, v51
	v_add_u32_e32 v154, v40, v52
	v_add_u32_e32 v155, v40, v53
	v_add_u32_e32 v156, v40, v54
	v_add_u32_e32 v157, v40, v55
	v_add_u32_e32 v158, v40, v56
	v_add_u32_e32 v159, v40, v57
	v_add_u32_e32 v160, v40, v58
	v_add_u32_e32 v161, v40, v59
	v_add_u32_e32 v162, v40, v60
	v_add_u32_e32 v163, v40, v38
	v_add_u32_e32 v164, v41, v62
	v_add_u32_e32 v165, v41, v63
	v_add_u32_e32 v166, v41, v61
	v_add_u32_e32 v167, v41, v45
	v_add_u32_e32 v168, v41, v64
	v_add_u32_e32 v169, v41, v65
	v_add_u32_e32 v170, v41, v66
	v_add_u32_e32 v171, v41, v67
	s_mov_b32 s11, s7
	s_mov_b32 s18, s7
	s_waitcnt vmcnt(0)
	s_branch .LBB0_333
.LBB0_331:
	v_mul_lo_u32 v0, s0, v123
	v_add_u32_e32 v24, s20, v0
	v_ashrrev_i32_e32 v25, 31, v24
	v_lshlrev_b64 v[0:1], 11, v[24:25]
	v_add_u32_e32 v8, 1, v24
	v_add_u32_e32 v16, 2, v24
	v_add_u32_e32 v24, 3, v24
	v_readlane_b32 s4, v254, 31
	v_ashrrev_i32_e32 v9, 31, v8
	v_ashrrev_i32_e32 v17, 31, v16
	v_ashrrev_i32_e32 v25, 31, v24
	v_readlane_b32 s5, v254, 32
	s_lshl_b32 s0, s19, 7
	v_lshlrev_b64 v[8:9], 11, v[8:9]
	v_lshlrev_b64 v[16:17], 11, v[16:17]
	v_lshlrev_b64 v[24:25], 11, v[24:25]
	v_lshl_add_u64 v[0:1], s[4:5], 0, v[0:1]
	s_and_b32 s36, s0, 0x380
	v_lshl_add_u64 v[8:9], s[4:5], 0, v[8:9]
	v_lshl_add_u64 v[16:17], s[4:5], 0, v[16:17]
	v_lshl_add_u64 v[24:25], s[4:5], 0, v[24:25]
	v_lshl_add_u64 v[0:1], v[0:1], 0, s[36:37]
	v_lshl_add_u64 v[8:9], v[8:9], 0, s[36:37]
	v_lshl_add_u64 v[16:17], v[16:17], 0, s[36:37]
	v_lshl_add_u64 v[24:25], v[24:25], 0, s[36:37]
	v_lshl_add_u64 v[0:1], v[0:1], 0, v[208:209]
	v_lshl_add_u64 v[8:9], v[8:9], 0, v[208:209]
	v_lshl_add_u64 v[16:17], v[16:17], 0, v[208:209]
	v_lshl_add_u64 v[24:25], v[24:25], 0, v[208:209]
	ds_read_b64_tr_b16 v[110:111], v144 offset:36928
	ds_read_b64_tr_b16 v[108:109], v144 offset:34816
	ds_read_b64_tr_b16 v[112:113], v144 offset:34848
	ds_read_b64_tr_b16 v[100:101], v144 offset:51712
	ds_read_b64_tr_b16 v[102:103], v144 offset:53824
	ds_read_b64_tr_b16 v[46:47], v145 offset:36928
	ds_read_b64_tr_b16 v[44:45], v145 offset:34816
	ds_read_b64_tr_b16 v[96:97], v145 offset:34848
	ds_read_b64_tr_b16 v[42:43], v146 offset:36928
	ds_read_b64_tr_b16 v[40:41], v146 offset:34816
	ds_read_b64_tr_b16 v[88:89], v146 offset:34848
	ds_read_b64_tr_b16 v[114:115], v144 offset:36960
	ds_read_b64_tr_b16 v[104:105], v144 offset:51744
	ds_read_b64_tr_b16 v[106:107], v144 offset:53856
	ds_read_b64_tr_b16 v[98:99], v145 offset:36960
	ds_read_b64_tr_b16 v[90:91], v146 offset:36960
	s_add_i32 s0, s16, s2
	s_and_b64 s[20:21], s[42:43], exec
	s_movk_i32 s1, 0xfff
	s_cselect_b32 s1, s1, 0xff
	s_mul_i32 s16, s0, 13
	s_add_i32 s10, s10, 1
	s_add_i32 s11, s11, s54
	ds_read_b128 v[176:179], v147
	ds_read_b128 v[180:183], v147 offset:64
	ds_read_b128 v[184:187], v147 offset:128
	ds_read_b128 v[188:191], v147 offset:192
	ds_read_b128 v[192:195], v147 offset:4352
	ds_read_b128 v[196:199], v147 offset:4416
	s_waitcnt lgkmcnt(5)
	v_mfma_f32_16x16x32_bf16 v[84:87], v[176:179], v[108:111], 0
	v_mfma_f32_16x16x32_bf16 v[80:83], v[176:179], v[112:115], 0
	ds_read_b128 v[176:179], v147 offset:4480
	s_waitcnt lgkmcnt(5)
	v_mfma_f32_16x16x32_bf16 v[84:87], v[180:183], v[100:103], v[84:87]
	v_mfma_f32_16x16x32_bf16 v[80:83], v[180:183], v[104:107], v[80:83]
	ds_read_b128 v[180:183], v147 offset:4544
	s_waitcnt lgkmcnt(5)
	v_mfma_f32_16x16x32_bf16 v[84:87], v[184:187], v[44:47], v[84:87]
	v_mfma_f32_16x16x32_bf16 v[80:83], v[184:187], v[96:99], v[80:83]
	ds_read_b128 v[184:187], v147 offset:8704
	s_waitcnt lgkmcnt(5)
	v_mfma_f32_16x16x32_bf16 v[84:87], v[188:191], v[40:43], v[84:87]
	v_mfma_f32_16x16x32_bf16 v[80:83], v[188:191], v[88:91], v[80:83]
	ds_read_b128 v[188:191], v147 offset:8768
	global_load_dwordx4 v[4:7], v[0:1], off
	s_waitcnt lgkmcnt(5)
	v_mfma_f32_16x16x32_bf16 v[68:71], v[192:195], v[108:111], 0
	v_mfma_f32_16x16x32_bf16 v[64:67], v[192:195], v[112:115], 0
	ds_read_b128 v[192:195], v147 offset:8832
	s_waitcnt lgkmcnt(5)
	v_mfma_f32_16x16x32_bf16 v[68:71], v[196:199], v[100:103], v[68:71]
	v_mfma_f32_16x16x32_bf16 v[64:67], v[196:199], v[104:107], v[64:67]
	ds_read_b128 v[196:199], v147 offset:8896
	s_waitcnt lgkmcnt(5)
	v_mfma_f32_16x16x32_bf16 v[68:71], v[176:179], v[44:47], v[68:71]
	v_mfma_f32_16x16x32_bf16 v[64:67], v[176:179], v[96:99], v[64:67]
	ds_read_b128 v[176:179], v147 offset:13056
	s_waitcnt lgkmcnt(5)
	v_mfma_f32_16x16x32_bf16 v[68:71], v[180:183], v[40:43], v[68:71]
	v_mfma_f32_16x16x32_bf16 v[64:67], v[180:183], v[88:91], v[64:67]
	ds_read_b128 v[180:183], v147 offset:13120
	global_load_dwordx4 v[0:3], v[0:1], off offset:1024
	s_waitcnt lgkmcnt(5)
	v_mfma_f32_16x16x32_bf16 v[52:55], v[184:187], v[108:111], 0
	v_mfma_f32_16x16x32_bf16 v[48:51], v[184:187], v[112:115], 0
	ds_read_b128 v[184:187], v147 offset:13184
	s_waitcnt lgkmcnt(5)
	v_mfma_f32_16x16x32_bf16 v[52:55], v[188:191], v[100:103], v[52:55]
	v_mfma_f32_16x16x32_bf16 v[48:51], v[188:191], v[104:107], v[48:51]
	ds_read_b128 v[188:191], v147 offset:13248
	s_waitcnt lgkmcnt(5)
	v_mfma_f32_16x16x32_bf16 v[52:55], v[192:195], v[44:47], v[52:55]
	v_mfma_f32_16x16x32_bf16 v[48:51], v[192:195], v[96:99], v[48:51]
	ds_read_b128 v[192:195], v147 offset:17408
	s_waitcnt lgkmcnt(5)
	v_mfma_f32_16x16x32_bf16 v[52:55], v[196:199], v[40:43], v[52:55]
	v_mfma_f32_16x16x32_bf16 v[48:51], v[196:199], v[88:91], v[48:51]
	ds_read_b128 v[196:199], v147 offset:17472
	global_load_dwordx4 v[12:15], v[8:9], off
	s_waitcnt lgkmcnt(5)
	v_mfma_f32_16x16x32_bf16 v[36:39], v[176:179], v[108:111], 0
	v_mfma_f32_16x16x32_bf16 v[32:35], v[176:179], v[112:115], 0
	ds_read_b128 v[176:179], v147 offset:17536
	s_waitcnt lgkmcnt(5)
	v_mfma_f32_16x16x32_bf16 v[36:39], v[180:183], v[100:103], v[36:39]
	v_mfma_f32_16x16x32_bf16 v[32:35], v[180:183], v[104:107], v[32:35]
	ds_read_b128 v[180:183], v147 offset:17600
	s_waitcnt lgkmcnt(5)
	v_mfma_f32_16x16x32_bf16 v[36:39], v[184:187], v[44:47], v[36:39]
	v_mfma_f32_16x16x32_bf16 v[32:35], v[184:187], v[96:99], v[32:35]
	ds_read_b128 v[184:187], v147 offset:21760
	s_waitcnt lgkmcnt(5)
	v_mfma_f32_16x16x32_bf16 v[36:39], v[188:191], v[40:43], v[36:39]
	v_mfma_f32_16x16x32_bf16 v[32:35], v[188:191], v[88:91], v[32:35]
	ds_read_b128 v[188:191], v147 offset:21824
	global_load_dwordx4 v[8:11], v[8:9], off offset:1024
	s_waitcnt lgkmcnt(5)
	v_mfma_f32_16x16x32_bf16 v[116:119], v[192:195], v[108:111], 0
	v_mfma_f32_16x16x32_bf16 v[92:95], v[192:195], v[112:115], 0
	ds_read_b128 v[192:195], v147 offset:21888
	s_waitcnt lgkmcnt(5)
	v_mfma_f32_16x16x32_bf16 v[116:119], v[196:199], v[100:103], v[116:119]
	v_mfma_f32_16x16x32_bf16 v[92:95], v[196:199], v[104:107], v[92:95]
	ds_read_b128 v[196:199], v147 offset:21952
	s_waitcnt lgkmcnt(5)
	v_mfma_f32_16x16x32_bf16 v[116:119], v[176:179], v[44:47], v[116:119]
	v_mfma_f32_16x16x32_bf16 v[92:95], v[176:179], v[96:99], v[92:95]
	ds_read_b128 v[176:179], v147 offset:26112
	s_waitcnt lgkmcnt(5)
	v_mfma_f32_16x16x32_bf16 v[116:119], v[180:183], v[40:43], v[116:119]
	v_mfma_f32_16x16x32_bf16 v[92:95], v[180:183], v[88:91], v[92:95]
	ds_read_b128 v[180:183], v147 offset:26176
	global_load_dwordx4 v[20:23], v[16:17], off
	s_waitcnt lgkmcnt(5)
	v_mfma_f32_16x16x32_bf16 v[76:79], v[184:187], v[108:111], 0
	v_mfma_f32_16x16x32_bf16 v[72:75], v[184:187], v[112:115], 0
	ds_read_b128 v[184:187], v147 offset:26240
	s_waitcnt lgkmcnt(5)
	v_mfma_f32_16x16x32_bf16 v[76:79], v[188:191], v[100:103], v[76:79]
	v_mfma_f32_16x16x32_bf16 v[72:75], v[188:191], v[104:107], v[72:75]
	ds_read_b128 v[188:191], v147 offset:26304
	s_waitcnt lgkmcnt(5)
	v_mfma_f32_16x16x32_bf16 v[76:79], v[192:195], v[44:47], v[76:79]
	v_mfma_f32_16x16x32_bf16 v[72:75], v[192:195], v[96:99], v[72:75]
	ds_read_b128 v[192:195], v147 offset:30464
	s_waitcnt lgkmcnt(5)
	v_mfma_f32_16x16x32_bf16 v[76:79], v[196:199], v[40:43], v[76:79]
	v_mfma_f32_16x16x32_bf16 v[72:75], v[196:199], v[88:91], v[72:75]
	ds_read_b128 v[196:199], v147 offset:30528
	global_load_dwordx4 v[16:19], v[16:17], off offset:1024
	s_waitcnt lgkmcnt(5)
	v_mfma_f32_16x16x32_bf16 v[60:63], v[176:179], v[108:111], 0
	v_mfma_f32_16x16x32_bf16 v[56:59], v[176:179], v[112:115], 0
	ds_read_b128 v[176:179], v147 offset:30592
	s_waitcnt lgkmcnt(5)
	v_mfma_f32_16x16x32_bf16 v[60:63], v[180:183], v[100:103], v[60:63]
	v_mfma_f32_16x16x32_bf16 v[56:59], v[180:183], v[104:107], v[56:59]
	ds_read_b128 v[180:183], v147 offset:30656
	s_waitcnt lgkmcnt(5)
	v_mfma_f32_16x16x32_bf16 v[60:63], v[184:187], v[44:47], v[60:63]
	v_mfma_f32_16x16x32_bf16 v[56:59], v[184:187], v[96:99], v[56:59]
	s_waitcnt lgkmcnt(4)
	v_mfma_f32_16x16x32_bf16 v[60:63], v[188:191], v[40:43], v[60:63]
	v_mfma_f32_16x16x32_bf16 v[56:59], v[188:191], v[88:91], v[56:59]
	global_load_dwordx4 v[28:31], v[24:25], off
	s_waitcnt lgkmcnt(3)
	v_mfma_f32_16x16x32_bf16 v[108:111], v[192:195], v[108:111], 0
	v_mfma_f32_16x16x32_bf16 v[112:115], v[192:195], v[112:115], 0
	s_waitcnt lgkmcnt(2)
	v_mfma_f32_16x16x32_bf16 v[100:103], v[196:199], v[100:103], v[108:111]
	v_mfma_f32_16x16x32_bf16 v[104:107], v[196:199], v[104:107], v[112:115]
	s_waitcnt lgkmcnt(1)
	v_mfma_f32_16x16x32_bf16 v[44:47], v[176:179], v[44:47], v[100:103]
	v_mfma_f32_16x16x32_bf16 v[96:99], v[176:179], v[96:99], v[104:107]
	s_waitcnt lgkmcnt(0)
	s_barrier
	v_mfma_f32_16x16x32_bf16 v[44:47], v[180:183], v[40:43], v[44:47]
	v_mfma_f32_16x16x32_bf16 v[40:43], v[180:183], v[88:91], v[96:99]
	global_load_dwordx4 v[24:27], v[24:25], off offset:1024
	s_branch .Lffta_tw
.LBB0_332:
	ds_read_b64_tr_b16 v[110:111], v144 offset:36928
	ds_read_b64_tr_b16 v[108:109], v144 offset:34816
	ds_read_b64_tr_b16 v[112:113], v144 offset:34848
	ds_read_b64_tr_b16 v[100:101], v144 offset:51712
	ds_read_b64_tr_b16 v[102:103], v144 offset:53824
	ds_read_b64_tr_b16 v[46:47], v145 offset:36928
	ds_read_b64_tr_b16 v[44:45], v145 offset:34816
	ds_read_b64_tr_b16 v[96:97], v145 offset:34848
	ds_read_b64_tr_b16 v[42:43], v146 offset:36928
	ds_read_b64_tr_b16 v[40:41], v146 offset:34816
	ds_read_b64_tr_b16 v[88:89], v146 offset:34848
	ds_read_b64_tr_b16 v[114:115], v144 offset:36960
	ds_read_b64_tr_b16 v[104:105], v144 offset:51744
	ds_read_b64_tr_b16 v[106:107], v144 offset:53856
	ds_read_b64_tr_b16 v[98:99], v145 offset:36960
	ds_read_b64_tr_b16 v[90:91], v146 offset:36960
	s_add_i32 s0, s16, s2
	s_and_b64 s[20:21], s[42:43], exec
	s_movk_i32 s1, 0xfff
	s_cselect_b32 s1, s1, 0xff
	s_mul_i32 s16, s0, 13
	s_add_i32 s10, s10, 1
	s_add_i32 s11, s11, s54
	ds_read_b128 v[176:179], v147
	ds_read_b128 v[180:183], v147 offset:64
	ds_read_b128 v[184:187], v147 offset:128
	ds_read_b128 v[188:191], v147 offset:192
	ds_read_b128 v[192:195], v147 offset:4352
	ds_read_b128 v[196:199], v147 offset:4416
	s_waitcnt lgkmcnt(5)
	v_mfma_f32_16x16x32_bf16 v[84:87], v[176:179], v[108:111], 0
	v_mfma_f32_16x16x32_bf16 v[80:83], v[176:179], v[112:115], 0
	ds_read_b128 v[176:179], v147 offset:4480
	s_waitcnt lgkmcnt(5)
	v_mfma_f32_16x16x32_bf16 v[84:87], v[180:183], v[100:103], v[84:87]
	v_mfma_f32_16x16x32_bf16 v[80:83], v[180:183], v[104:107], v[80:83]
	ds_read_b128 v[180:183], v147 offset:4544
	s_waitcnt lgkmcnt(5)
	v_mfma_f32_16x16x32_bf16 v[84:87], v[184:187], v[44:47], v[84:87]
	v_mfma_f32_16x16x32_bf16 v[80:83], v[184:187], v[96:99], v[80:83]
	ds_read_b128 v[184:187], v147 offset:8704
	s_waitcnt lgkmcnt(5)
	v_mfma_f32_16x16x32_bf16 v[84:87], v[188:191], v[40:43], v[84:87]
	v_mfma_f32_16x16x32_bf16 v[80:83], v[188:191], v[88:91], v[80:83]
	ds_read_b128 v[188:191], v147 offset:8768
	s_waitcnt lgkmcnt(5)
	v_mfma_f32_16x16x32_bf16 v[68:71], v[192:195], v[108:111], 0
	v_mfma_f32_16x16x32_bf16 v[64:67], v[192:195], v[112:115], 0
	ds_read_b128 v[192:195], v147 offset:8832
	s_waitcnt lgkmcnt(5)
	v_mfma_f32_16x16x32_bf16 v[68:71], v[196:199], v[100:103], v[68:71]
	v_mfma_f32_16x16x32_bf16 v[64:67], v[196:199], v[104:107], v[64:67]
	ds_read_b128 v[196:199], v147 offset:8896
	s_waitcnt lgkmcnt(5)
	v_mfma_f32_16x16x32_bf16 v[68:71], v[176:179], v[44:47], v[68:71]
	v_mfma_f32_16x16x32_bf16 v[64:67], v[176:179], v[96:99], v[64:67]
	ds_read_b128 v[176:179], v147 offset:13056
	s_waitcnt lgkmcnt(5)
	v_mfma_f32_16x16x32_bf16 v[68:71], v[180:183], v[40:43], v[68:71]
	v_mfma_f32_16x16x32_bf16 v[64:67], v[180:183], v[88:91], v[64:67]
	ds_read_b128 v[180:183], v147 offset:13120
	s_waitcnt lgkmcnt(5)
	v_mfma_f32_16x16x32_bf16 v[52:55], v[184:187], v[108:111], 0
	v_mfma_f32_16x16x32_bf16 v[48:51], v[184:187], v[112:115], 0
	ds_read_b128 v[184:187], v147 offset:13184
	s_waitcnt lgkmcnt(5)
	v_mfma_f32_16x16x32_bf16 v[52:55], v[188:191], v[100:103], v[52:55]
	v_mfma_f32_16x16x32_bf16 v[48:51], v[188:191], v[104:107], v[48:51]
	ds_read_b128 v[188:191], v147 offset:13248
	s_waitcnt lgkmcnt(5)
	v_mfma_f32_16x16x32_bf16 v[52:55], v[192:195], v[44:47], v[52:55]
	v_mfma_f32_16x16x32_bf16 v[48:51], v[192:195], v[96:99], v[48:51]
	ds_read_b128 v[192:195], v147 offset:17408
	s_waitcnt lgkmcnt(5)
	v_mfma_f32_16x16x32_bf16 v[52:55], v[196:199], v[40:43], v[52:55]
	v_mfma_f32_16x16x32_bf16 v[48:51], v[196:199], v[88:91], v[48:51]
	ds_read_b128 v[196:199], v147 offset:17472
	s_waitcnt lgkmcnt(5)
	v_mfma_f32_16x16x32_bf16 v[36:39], v[176:179], v[108:111], 0
	v_mfma_f32_16x16x32_bf16 v[32:35], v[176:179], v[112:115], 0
	ds_read_b128 v[176:179], v147 offset:17536
	s_waitcnt lgkmcnt(5)
	v_mfma_f32_16x16x32_bf16 v[36:39], v[180:183], v[100:103], v[36:39]
	v_mfma_f32_16x16x32_bf16 v[32:35], v[180:183], v[104:107], v[32:35]
	ds_read_b128 v[180:183], v147 offset:17600
	s_waitcnt lgkmcnt(5)
	v_mfma_f32_16x16x32_bf16 v[36:39], v[184:187], v[44:47], v[36:39]
	v_mfma_f32_16x16x32_bf16 v[32:35], v[184:187], v[96:99], v[32:35]
	ds_read_b128 v[184:187], v147 offset:21760
	s_waitcnt lgkmcnt(5)
	v_mfma_f32_16x16x32_bf16 v[36:39], v[188:191], v[40:43], v[36:39]
	v_mfma_f32_16x16x32_bf16 v[32:35], v[188:191], v[88:91], v[32:35]
	ds_read_b128 v[188:191], v147 offset:21824
	s_waitcnt lgkmcnt(5)
	v_mfma_f32_16x16x32_bf16 v[116:119], v[192:195], v[108:111], 0
	v_mfma_f32_16x16x32_bf16 v[92:95], v[192:195], v[112:115], 0
	ds_read_b128 v[192:195], v147 offset:21888
	s_waitcnt lgkmcnt(5)
	v_mfma_f32_16x16x32_bf16 v[116:119], v[196:199], v[100:103], v[116:119]
	v_mfma_f32_16x16x32_bf16 v[92:95], v[196:199], v[104:107], v[92:95]
	ds_read_b128 v[196:199], v147 offset:21952
	s_waitcnt lgkmcnt(5)
	v_mfma_f32_16x16x32_bf16 v[116:119], v[176:179], v[44:47], v[116:119]
	v_mfma_f32_16x16x32_bf16 v[92:95], v[176:179], v[96:99], v[92:95]
	ds_read_b128 v[176:179], v147 offset:26112
	s_waitcnt lgkmcnt(5)
	v_mfma_f32_16x16x32_bf16 v[116:119], v[180:183], v[40:43], v[116:119]
	v_mfma_f32_16x16x32_bf16 v[92:95], v[180:183], v[88:91], v[92:95]
	ds_read_b128 v[180:183], v147 offset:26176
	s_waitcnt lgkmcnt(5)
	v_mfma_f32_16x16x32_bf16 v[76:79], v[184:187], v[108:111], 0
	v_mfma_f32_16x16x32_bf16 v[72:75], v[184:187], v[112:115], 0
	ds_read_b128 v[184:187], v147 offset:26240
	s_waitcnt lgkmcnt(5)
	v_mfma_f32_16x16x32_bf16 v[76:79], v[188:191], v[100:103], v[76:79]
	v_mfma_f32_16x16x32_bf16 v[72:75], v[188:191], v[104:107], v[72:75]
	ds_read_b128 v[188:191], v147 offset:26304
	s_waitcnt lgkmcnt(5)
	v_mfma_f32_16x16x32_bf16 v[76:79], v[192:195], v[44:47], v[76:79]
	v_mfma_f32_16x16x32_bf16 v[72:75], v[192:195], v[96:99], v[72:75]
	ds_read_b128 v[192:195], v147 offset:30464
	s_waitcnt lgkmcnt(5)
	v_mfma_f32_16x16x32_bf16 v[76:79], v[196:199], v[40:43], v[76:79]
	v_mfma_f32_16x16x32_bf16 v[72:75], v[196:199], v[88:91], v[72:75]
	ds_read_b128 v[196:199], v147 offset:30528
	s_waitcnt lgkmcnt(5)
	v_mfma_f32_16x16x32_bf16 v[60:63], v[176:179], v[108:111], 0
	v_mfma_f32_16x16x32_bf16 v[56:59], v[176:179], v[112:115], 0
	ds_read_b128 v[176:179], v147 offset:30592
	s_waitcnt lgkmcnt(5)
	v_mfma_f32_16x16x32_bf16 v[60:63], v[180:183], v[100:103], v[60:63]
	v_mfma_f32_16x16x32_bf16 v[56:59], v[180:183], v[104:107], v[56:59]
	ds_read_b128 v[180:183], v147 offset:30656
	s_waitcnt lgkmcnt(5)
	v_mfma_f32_16x16x32_bf16 v[60:63], v[184:187], v[44:47], v[60:63]
	v_mfma_f32_16x16x32_bf16 v[56:59], v[184:187], v[96:99], v[56:59]
	s_waitcnt lgkmcnt(4)
	v_mfma_f32_16x16x32_bf16 v[60:63], v[188:191], v[40:43], v[60:63]
	v_mfma_f32_16x16x32_bf16 v[56:59], v[188:191], v[88:91], v[56:59]
	s_waitcnt lgkmcnt(3)
	v_mfma_f32_16x16x32_bf16 v[108:111], v[192:195], v[108:111], 0
	v_mfma_f32_16x16x32_bf16 v[112:115], v[192:195], v[112:115], 0
	s_waitcnt lgkmcnt(2)
	v_mfma_f32_16x16x32_bf16 v[100:103], v[196:199], v[100:103], v[108:111]
	v_mfma_f32_16x16x32_bf16 v[104:107], v[196:199], v[104:107], v[112:115]
	s_waitcnt lgkmcnt(1)
	v_mfma_f32_16x16x32_bf16 v[44:47], v[176:179], v[44:47], v[100:103]
	v_mfma_f32_16x16x32_bf16 v[96:99], v[176:179], v[96:99], v[104:107]
	s_waitcnt lgkmcnt(0)
	s_barrier
	v_mfma_f32_16x16x32_bf16 v[44:47], v[180:183], v[40:43], v[44:47]
	v_mfma_f32_16x16x32_bf16 v[40:43], v[180:183], v[88:91], v[96:99]
.Lffta_tw:
	v_mov_b32_e32 v88, 0x3b800000
	v_mov_b32_e32 v89, 0x39800000
	v_cndmask_b32_e64 v88, v88, v89, s[42:43]
	v_mul_lo_u32 v89, s0, v125
	v_and_b32_e32 v90, s1, v89
	v_cvt_f32_u32_e32 v90, v90
	v_mul_f32_e32 v90, v88, v90
	v_cos_f32_e32 v91, v90
	v_sin_f32_e32 v90, v90
	s_nop 0
	v_mul_f32_e32 v96, v90, v116
	v_fmac_f32_e32 v96, v91, v84
	v_bfe_u32 v97, v96, 16, 1
	v_mul_f32_e32 v84, v90, v84
	v_add3_u32 v96, v96, v97, s3
	v_fma_f32 v84, v91, v116, -v84
	ds_write_b16_d16_hi v148, v96 offset:34816
	v_bfe_u32 v96, v84, 16, 1
	v_add3_u32 v84, v84, v96, s3
	ds_write_b16_d16_hi v148, v84 offset:34944
	v_mul_f32_e32 v84, v90, v92
	v_fmac_f32_e32 v84, v91, v80
	v_bfe_u32 v96, v84, 16, 1
	v_mul_f32_e32 v80, v90, v80
	v_add3_u32 v84, v84, v96, s3
	v_fma_f32 v80, v91, v92, -v80
	ds_write_b16_d16_hi v148, v84 offset:34848
	v_bfe_u32 v84, v80, 16, 1
	v_add3_u32 v80, v80, v84, s3
	ds_write_b16_d16_hi v148, v80 offset:34976
	v_add_u32_e32 v80, s0, v89
	v_and_b32_e32 v84, s1, v80
	v_cvt_f32_u32_e32 v84, v84
	v_add_u32_e32 v80, s0, v80
	v_mul_f32_e32 v84, v88, v84
	v_cos_f32_e32 v89, v84
	v_sin_f32_e32 v84, v84
	s_nop 0
	v_mul_f32_e32 v90, v84, v117
	v_fmac_f32_e32 v90, v89, v85
	v_bfe_u32 v91, v90, 16, 1
	v_mul_f32_e32 v85, v84, v85
	v_add3_u32 v90, v90, v91, s3
	v_fma_f32 v85, v89, v117, -v85
	ds_write_b16_d16_hi v149, v90 offset:34816
	v_bfe_u32 v90, v85, 16, 1
	v_add3_u32 v85, v85, v90, s3
	ds_write_b16_d16_hi v149, v85 offset:34944
	v_mul_f32_e32 v85, v84, v93
	v_fmac_f32_e32 v85, v89, v81
	v_mul_f32_e32 v81, v84, v81
	v_fma_f32 v81, v89, v93, -v81
	v_bfe_u32 v84, v81, 16, 1
	v_add3_u32 v81, v81, v84, s3
	ds_write_b16_d16_hi v149, v81 offset:34976
	v_and_b32_e32 v81, s1, v80
	v_cvt_f32_u32_e32 v81, v81
	v_bfe_u32 v90, v85, 16, 1
	v_add3_u32 v85, v85, v90, s3
	ds_write_b16_d16_hi v149, v85 offset:34848
	v_mul_f32_e32 v81, v88, v81
	v_cos_f32_e32 v84, v81
	v_sin_f32_e32 v81, v81
	v_add_u32_e32 v80, s0, v80
	v_mul_f32_e32 v85, v81, v118
	v_fmac_f32_e32 v85, v84, v86
	v_bfe_u32 v89, v85, 16, 1
	v_add3_u32 v85, v85, v89, s3
	ds_write_b16_d16_hi v150, v85 offset:34816
	v_mul_f32_e32 v85, v81, v86
	v_fma_f32 v85, v84, v118, -v85
	v_bfe_u32 v86, v85, 16, 1
	v_add3_u32 v85, v85, v86, s3
	ds_write_b16_d16_hi v150, v85 offset:34944
	v_mul_f32_e32 v85, v81, v94
	v_mul_f32_e32 v81, v81, v82
	v_fma_f32 v81, v84, v94, -v81
	v_fmac_f32_e32 v85, v84, v82
	v_bfe_u32 v82, v81, 16, 1
	v_add3_u32 v81, v81, v82, s3
	ds_write_b16_d16_hi v150, v81 offset:34976
	v_and_b32_e32 v81, s1, v80
	v_cvt_f32_u32_e32 v81, v81
	v_bfe_u32 v86, v85, 16, 1
	v_add3_u32 v85, v85, v86, s3
	ds_write_b16_d16_hi v150, v85 offset:34848
	v_mul_f32_e32 v81, v88, v81
	v_cos_f32_e32 v82, v81
	v_sin_f32_e32 v81, v81
	v_add_u32_e32 v80, s16, v80
	v_mul_f32_e32 v84, v81, v119
	v_fmac_f32_e32 v84, v82, v87
	v_bfe_u32 v85, v84, 16, 1
	v_add3_u32 v84, v84, v85, s3
	ds_write_b16_d16_hi v151, v84 offset:34816
	v_mul_f32_e32 v84, v81, v87
	v_fma_f32 v84, v82, v119, -v84
	v_bfe_u32 v85, v84, 16, 1
	v_add3_u32 v84, v84, v85, s3
	ds_write_b16_d16_hi v151, v84 offset:34944
	v_mul_f32_e32 v84, v81, v95
	v_mul_f32_e32 v81, v81, v83
	v_fma_f32 v81, v82, v95, -v81
	v_fmac_f32_e32 v84, v82, v83
	v_bfe_u32 v82, v81, 16, 1
	v_add3_u32 v81, v81, v82, s3
	ds_write_b16_d16_hi v151, v81 offset:34976
	v_and_b32_e32 v81, s1, v80
	v_cvt_f32_u32_e32 v81, v81
	v_bfe_u32 v85, v84, 16, 1
	v_add3_u32 v84, v84, v85, s3
	ds_write_b16_d16_hi v151, v84 offset:34848
	v_mul_f32_e32 v81, v88, v81
	v_cos_f32_e32 v82, v81
	v_sin_f32_e32 v81, v81
	s_nop 0
	v_mul_f32_e32 v83, v81, v76
	v_fmac_f32_e32 v83, v82, v68
	v_mul_f32_e32 v68, v81, v68
	v_fma_f32 v68, v82, v76, -v68
	v_bfe_u32 v76, v68, 16, 1
	v_add3_u32 v68, v68, v76, s3
	ds_write_b16_d16_hi v152, v68 offset:34944
	v_mul_f32_e32 v68, v81, v72
	v_fmac_f32_e32 v68, v82, v64
	v_bfe_u32 v76, v68, 16, 1
	v_mul_f32_e32 v64, v81, v64
	v_add3_u32 v68, v68, v76, s3
	v_fma_f32 v64, v82, v72, -v64
	ds_write_b16_d16_hi v152, v68 offset:34848
	v_bfe_u32 v68, v64, 16, 1
	v_add3_u32 v64, v64, v68, s3
	ds_write_b16_d16_hi v152, v64 offset:34976
	v_add_u32_e32 v64, s0, v80
	v_and_b32_e32 v68, s1, v64
	v_cvt_f32_u32_e32 v68, v68
	v_add_u32_e32 v64, s0, v64
	v_bfe_u32 v84, v83, 16, 1
	v_add3_u32 v83, v83, v84, s3
	v_mul_f32_e32 v68, v88, v68
	v_cos_f32_e32 v72, v68
	v_sin_f32_e32 v68, v68
	ds_write_b16_d16_hi v152, v83 offset:34816
	v_mul_f32_e32 v76, v68, v77
	v_fmac_f32_e32 v76, v72, v69
	v_bfe_u32 v80, v76, 16, 1
	v_mul_f32_e32 v69, v68, v69
	v_add3_u32 v76, v76, v80, s3
	v_fma_f32 v69, v72, v77, -v69
	ds_write_b16_d16_hi v153, v76 offset:34816
	v_bfe_u32 v76, v69, 16, 1
	v_add3_u32 v69, v69, v76, s3
	ds_write_b16_d16_hi v153, v69 offset:34944
	v_mul_f32_e32 v69, v68, v73
	v_fmac_f32_e32 v69, v72, v65
	v_mul_f32_e32 v65, v68, v65
	v_fma_f32 v65, v72, v73, -v65
	v_bfe_u32 v68, v65, 16, 1
	v_add3_u32 v65, v65, v68, s3
	ds_write_b16_d16_hi v153, v65 offset:34976
	v_and_b32_e32 v65, s1, v64
	v_cvt_f32_u32_e32 v65, v65
	v_bfe_u32 v76, v69, 16, 1
	v_add3_u32 v69, v69, v76, s3
	ds_write_b16_d16_hi v153, v69 offset:34848
	v_mul_f32_e32 v65, v88, v65
	v_cos_f32_e32 v68, v65
	v_sin_f32_e32 v65, v65
	v_add_u32_e32 v64, s0, v64
	v_mul_f32_e32 v69, v65, v78
	v_fmac_f32_e32 v69, v68, v70
	v_bfe_u32 v72, v69, 16, 1
	v_add3_u32 v69, v69, v72, s3
	ds_write_b16_d16_hi v154, v69 offset:34816
	v_mul_f32_e32 v69, v65, v70
	v_fma_f32 v69, v68, v78, -v69
	v_bfe_u32 v70, v69, 16, 1
	v_add3_u32 v69, v69, v70, s3
	ds_write_b16_d16_hi v154, v69 offset:34944
	v_mul_f32_e32 v69, v65, v74
	v_mul_f32_e32 v65, v65, v66
	v_fma_f32 v65, v68, v74, -v65
	v_fmac_f32_e32 v69, v68, v66
	v_bfe_u32 v66, v65, 16, 1
	v_add3_u32 v65, v65, v66, s3
	ds_write_b16_d16_hi v154, v65 offset:34976
	v_and_b32_e32 v65, s1, v64
	v_cvt_f32_u32_e32 v65, v65
	v_bfe_u32 v70, v69, 16, 1
	v_add3_u32 v69, v69, v70, s3
	ds_write_b16_d16_hi v154, v69 offset:34848
	v_mul_f32_e32 v65, v88, v65
	v_cos_f32_e32 v66, v65
	v_sin_f32_e32 v65, v65
	v_add_u32_e32 v64, s16, v64
	v_mul_f32_e32 v68, v65, v79
	v_fmac_f32_e32 v68, v66, v71
	v_bfe_u32 v69, v68, 16, 1
	v_add3_u32 v68, v68, v69, s3
	ds_write_b16_d16_hi v155, v68 offset:34816
	v_mul_f32_e32 v68, v65, v71
	v_fma_f32 v68, v66, v79, -v68
	v_bfe_u32 v69, v68, 16, 1
	v_add3_u32 v68, v68, v69, s3
	ds_write_b16_d16_hi v155, v68 offset:34944
	v_mul_f32_e32 v68, v65, v75
	v_mul_f32_e32 v65, v65, v67
	v_fma_f32 v65, v66, v75, -v65
	v_fmac_f32_e32 v68, v66, v67
	v_bfe_u32 v66, v65, 16, 1
	v_add3_u32 v65, v65, v66, s3
	ds_write_b16_d16_hi v155, v65 offset:34976
	v_and_b32_e32 v65, s1, v64
	v_cvt_f32_u32_e32 v65, v65
	v_bfe_u32 v69, v68, 16, 1
	v_add3_u32 v68, v68, v69, s3
	ds_write_b16_d16_hi v155, v68 offset:34848
	v_mul_f32_e32 v65, v88, v65
	v_cos_f32_e32 v66, v65
	v_sin_f32_e32 v65, v65
	s_nop 0
	v_mul_f32_e32 v67, v65, v60
	v_fmac_f32_e32 v67, v66, v52
	v_mul_f32_e32 v52, v65, v52
	v_fma_f32 v52, v66, v60, -v52
	v_bfe_u32 v60, v52, 16, 1
	v_add3_u32 v52, v52, v60, s3
	ds_write_b16_d16_hi v156, v52 offset:34944
	v_mul_f32_e32 v52, v65, v56
	v_fmac_f32_e32 v52, v66, v48
	v_bfe_u32 v60, v52, 16, 1
	v_mul_f32_e32 v48, v65, v48
	v_add3_u32 v52, v52, v60, s3
	v_fma_f32 v48, v66, v56, -v48
	ds_write_b16_d16_hi v156, v52 offset:34848
	v_bfe_u32 v52, v48, 16, 1
	v_add3_u32 v48, v48, v52, s3
	ds_write_b16_d16_hi v156, v48 offset:34976
	v_add_u32_e32 v48, s0, v64
	v_and_b32_e32 v52, s1, v48
	v_cvt_f32_u32_e32 v52, v52
	v_add_u32_e32 v48, s0, v48
	v_bfe_u32 v68, v67, 16, 1
	v_add3_u32 v67, v67, v68, s3
	v_mul_f32_e32 v52, v88, v52
	v_cos_f32_e32 v56, v52
	v_sin_f32_e32 v52, v52
	ds_write_b16_d16_hi v156, v67 offset:34816
	v_mul_f32_e32 v60, v52, v61
	v_fmac_f32_e32 v60, v56, v53
	v_bfe_u32 v64, v60, 16, 1
	v_mul_f32_e32 v53, v52, v53
	v_add3_u32 v60, v60, v64, s3
	v_fma_f32 v53, v56, v61, -v53
	ds_write_b16_d16_hi v157, v60 offset:34816
	v_bfe_u32 v60, v53, 16, 1
	v_add3_u32 v53, v53, v60, s3
	ds_write_b16_d16_hi v157, v53 offset:34944
	v_mul_f32_e32 v53, v52, v57
	v_fmac_f32_e32 v53, v56, v49
	v_mul_f32_e32 v49, v52, v49
	v_fma_f32 v49, v56, v57, -v49
	v_bfe_u32 v52, v49, 16, 1
	v_add3_u32 v49, v49, v52, s3
	ds_write_b16_d16_hi v157, v49 offset:34976
	v_and_b32_e32 v49, s1, v48
	v_cvt_f32_u32_e32 v49, v49
	v_bfe_u32 v60, v53, 16, 1
	v_add3_u32 v53, v53, v60, s3
	ds_write_b16_d16_hi v157, v53 offset:34848
	v_mul_f32_e32 v49, v88, v49
	v_cos_f32_e32 v52, v49
	v_sin_f32_e32 v49, v49
	v_add_u32_e32 v48, s0, v48
	v_mul_f32_e32 v53, v49, v62
	v_fmac_f32_e32 v53, v52, v54
	v_bfe_u32 v56, v53, 16, 1
	v_add3_u32 v53, v53, v56, s3
	ds_write_b16_d16_hi v158, v53 offset:34816
	v_mul_f32_e32 v53, v49, v54
	v_fma_f32 v53, v52, v62, -v53
	v_bfe_u32 v54, v53, 16, 1
	v_add3_u32 v53, v53, v54, s3
	ds_write_b16_d16_hi v158, v53 offset:34944
	v_mul_f32_e32 v53, v49, v58
	v_mul_f32_e32 v49, v49, v50
	v_fma_f32 v49, v52, v58, -v49
	v_fmac_f32_e32 v53, v52, v50
	v_bfe_u32 v50, v49, 16, 1
	v_add3_u32 v49, v49, v50, s3
	ds_write_b16_d16_hi v158, v49 offset:34976
	v_and_b32_e32 v49, s1, v48
	v_cvt_f32_u32_e32 v49, v49
	v_bfe_u32 v54, v53, 16, 1
	v_add3_u32 v53, v53, v54, s3
	ds_write_b16_d16_hi v158, v53 offset:34848
	v_mul_f32_e32 v49, v88, v49
	v_cos_f32_e32 v50, v49
	v_sin_f32_e32 v49, v49
	v_add_u32_e32 v48, s16, v48
	v_mul_f32_e32 v52, v49, v63
	v_fmac_f32_e32 v52, v50, v55
	v_bfe_u32 v53, v52, 16, 1
	v_add3_u32 v52, v52, v53, s3
	ds_write_b16_d16_hi v159, v52 offset:34816
	v_mul_f32_e32 v52, v49, v55
	v_fma_f32 v52, v50, v63, -v52
	v_bfe_u32 v53, v52, 16, 1
	v_add3_u32 v52, v52, v53, s3
	ds_write_b16_d16_hi v159, v52 offset:34944
	v_mul_f32_e32 v52, v49, v59
	v_mul_f32_e32 v49, v49, v51
	v_fma_f32 v49, v50, v59, -v49
	v_fmac_f32_e32 v52, v50, v51
	v_bfe_u32 v50, v49, 16, 1
	v_add3_u32 v49, v49, v50, s3
	ds_write_b16_d16_hi v159, v49 offset:34976
	v_and_b32_e32 v49, s1, v48
	v_cvt_f32_u32_e32 v49, v49
	v_bfe_u32 v53, v52, 16, 1
	v_add3_u32 v52, v52, v53, s3
	ds_write_b16_d16_hi v159, v52 offset:34848
	v_mul_f32_e32 v49, v88, v49
	v_cos_f32_e32 v50, v49
	v_sin_f32_e32 v49, v49
	s_nop 0
	v_mul_f32_e32 v51, v49, v44
	v_fmac_f32_e32 v51, v50, v36
	v_mul_f32_e32 v36, v49, v36
	v_fma_f32 v36, v50, v44, -v36
	v_bfe_u32 v44, v36, 16, 1
	v_add3_u32 v36, v36, v44, s3
	ds_write_b16_d16_hi v160, v36 offset:34944
	v_mul_f32_e32 v36, v49, v40
	v_fmac_f32_e32 v36, v50, v32
	v_bfe_u32 v44, v36, 16, 1
	v_mul_f32_e32 v32, v49, v32
	v_add3_u32 v36, v36, v44, s3
	v_fma_f32 v32, v50, v40, -v32
	ds_write_b16_d16_hi v160, v36 offset:34848
	v_bfe_u32 v36, v32, 16, 1
	v_add3_u32 v32, v32, v36, s3
	ds_write_b16_d16_hi v160, v32 offset:34976
	v_add_u32_e32 v32, s0, v48
	v_and_b32_e32 v36, s1, v32
	v_cvt_f32_u32_e32 v36, v36
	v_add_u32_e32 v32, s0, v32
	v_bfe_u32 v52, v51, 16, 1
	v_add3_u32 v51, v51, v52, s3
	v_mul_f32_e32 v36, v88, v36
	v_cos_f32_e32 v40, v36
	v_sin_f32_e32 v36, v36
	ds_write_b16_d16_hi v160, v51 offset:34816
	v_mul_f32_e32 v44, v36, v45
	v_fmac_f32_e32 v44, v40, v37
	v_bfe_u32 v48, v44, 16, 1
	v_mul_f32_e32 v37, v36, v37
	v_add3_u32 v44, v44, v48, s3
	v_fma_f32 v37, v40, v45, -v37
	ds_write_b16_d16_hi v161, v44 offset:34816
	v_bfe_u32 v44, v37, 16, 1
	v_add3_u32 v37, v37, v44, s3
	ds_write_b16_d16_hi v161, v37 offset:34944
	v_mul_f32_e32 v37, v36, v41
	v_fmac_f32_e32 v37, v40, v33
	v_mul_f32_e32 v33, v36, v33
	v_fma_f32 v33, v40, v41, -v33
	v_bfe_u32 v36, v33, 16, 1
	v_add3_u32 v33, v33, v36, s3
	ds_write_b16_d16_hi v161, v33 offset:34976
	v_and_b32_e32 v33, s1, v32
	v_cvt_f32_u32_e32 v33, v33
	v_bfe_u32 v44, v37, 16, 1
	v_add3_u32 v37, v37, v44, s3
	ds_write_b16_d16_hi v161, v37 offset:34848
	v_mul_f32_e32 v33, v88, v33
	v_cos_f32_e32 v36, v33
	v_sin_f32_e32 v33, v33
	v_add_u32_e32 v32, s0, v32
	v_and_b32_e32 v32, s1, v32
	v_cvt_f32_u32_e32 v32, v32
	v_mul_f32_e32 v37, v33, v46
	v_fmac_f32_e32 v37, v36, v38
	v_bfe_u32 v40, v37, 16, 1
	v_add3_u32 v37, v37, v40, s3
	ds_write_b16_d16_hi v162, v37 offset:34816
	v_mul_f32_e32 v37, v33, v38
	v_fma_f32 v37, v36, v46, -v37
	v_bfe_u32 v38, v37, 16, 1
	v_add3_u32 v37, v37, v38, s3
	ds_write_b16_d16_hi v162, v37 offset:34944
	v_mul_f32_e32 v37, v33, v42
	v_mul_f32_e32 v33, v33, v34
	v_fma_f32 v33, v36, v42, -v33
	v_fmac_f32_e32 v37, v36, v34
	v_bfe_u32 v34, v33, 16, 1
	v_add3_u32 v33, v33, v34, s3
	v_mul_f32_e32 v32, v88, v32
	ds_write_b16_d16_hi v162, v33 offset:34976
	v_cos_f32_e32 v33, v32
	v_sin_f32_e32 v32, v32
	v_bfe_u32 v38, v37, 16, 1
	v_add3_u32 v37, v37, v38, s3
	ds_write_b16_d16_hi v162, v37 offset:34848
	v_mul_f32_e32 v34, v32, v47
	v_fmac_f32_e32 v34, v33, v39
	v_bfe_u32 v36, v34, 16, 1
	v_add3_u32 v34, v34, v36, s3
	ds_write_b16_d16_hi v163, v34 offset:34816
	v_mul_f32_e32 v34, v32, v39
	v_fma_f32 v34, v33, v47, -v34
	v_bfe_u32 v36, v34, 16, 1
	v_add3_u32 v34, v34, v36, s3
	ds_write_b16_d16_hi v163, v34 offset:34944
	v_mul_f32_e32 v34, v32, v43
	v_mul_f32_e32 v32, v32, v35
	v_fmac_f32_e32 v34, v33, v35
	v_fma_f32 v32, v33, v43, -v32
	v_bfe_u32 v36, v34, 16, 1
	v_bfe_u32 v33, v32, 16, 1
	v_add3_u32 v34, v34, v36, s3
	v_add3_u32 v32, v32, v33, s3
	ds_write_b16_d16_hi v163, v34 offset:34848
	ds_write_b16_d16_hi v163, v32 offset:34976
	s_waitcnt lgkmcnt(0)
	s_barrier
	ds_read_b128 v[176:179], v164 offset:34816
	ds_read_b128 v[180:183], v165 offset:34816
	ds_read_b128 v[184:187], v166 offset:34816
	ds_read_b128 v[188:191], v167 offset:34816
	ds_read_b128 v[192:195], v168 offset:34816
	ds_read_b128 v[196:199], v169 offset:34816
	ds_read_b128 v[100:103], v170 offset:34816
	ds_read_b128 v[104:107], v171 offset:34816
	s_lshl_b32 s0, s18, 7
	s_and_b32 s36, s0, 0x380
	v_lshl_add_u64 v[36:37], v[120:121], 0, s[36:37]
	v_mul_u32_u24_e32 v38, s17, v128
	v_add3_u32 v38, s15, v127, v38
	v_ashrrev_i32_e32 v39, 31, v38
	v_lshlrev_b64 v[38:39], 11, v[38:39]
	v_lshl_add_u64 v[38:39], v[36:37], 0, v[38:39]
	s_waitcnt lgkmcnt(7)
	global_store_dwordx4 v[38:39], v[176:179], off
	v_mul_u32_u24_e32 v38, s17, v130
	v_add3_u32 v38, s15, v129, v38
	v_ashrrev_i32_e32 v39, 31, v38
	v_lshlrev_b64 v[38:39], 11, v[38:39]
	v_lshl_add_u64 v[38:39], v[36:37], 0, v[38:39]
	s_waitcnt lgkmcnt(6)
	global_store_dwordx4 v[38:39], v[180:183], off
	v_mul_u32_u24_e32 v38, s17, v132
	v_add3_u32 v38, s15, v131, v38
	v_ashrrev_i32_e32 v39, 31, v38
	v_lshlrev_b64 v[38:39], 11, v[38:39]
	v_lshl_add_u64 v[38:39], v[36:37], 0, v[38:39]
	s_waitcnt lgkmcnt(5)
	global_store_dwordx4 v[38:39], v[184:187], off
	v_mul_u32_u24_e32 v38, s17, v134
	v_add3_u32 v38, s15, v133, v38
	v_ashrrev_i32_e32 v39, 31, v38
	v_lshlrev_b64 v[38:39], 11, v[38:39]
	v_lshl_add_u64 v[38:39], v[36:37], 0, v[38:39]
	s_waitcnt lgkmcnt(4)
	global_store_dwordx4 v[38:39], v[188:191], off
	v_mul_u32_u24_e32 v38, s17, v136
	v_add3_u32 v38, s15, v135, v38
	v_ashrrev_i32_e32 v39, 31, v38
	v_lshlrev_b64 v[38:39], 11, v[38:39]
	v_lshl_add_u64 v[38:39], v[36:37], 0, v[38:39]
	s_waitcnt lgkmcnt(3)
	global_store_dwordx4 v[38:39], v[192:195], off
	v_mul_u32_u24_e32 v38, s17, v138
	v_add3_u32 v38, s15, v137, v38
	v_ashrrev_i32_e32 v39, 31, v38
	v_lshlrev_b64 v[38:39], 11, v[38:39]
	v_lshl_add_u64 v[38:39], v[36:37], 0, v[38:39]
	s_waitcnt lgkmcnt(2)
	global_store_dwordx4 v[38:39], v[196:199], off
	v_mul_u32_u24_e32 v38, s17, v140
	v_add3_u32 v38, s15, v139, v38
	v_ashrrev_i32_e32 v39, 31, v38
	v_lshlrev_b64 v[38:39], 11, v[38:39]
	v_lshl_add_u64 v[38:39], v[36:37], 0, v[38:39]
	s_waitcnt lgkmcnt(1)
	global_store_dwordx4 v[38:39], v[100:103], off
	v_mul_u32_u24_e32 v38, s17, v142
	v_add3_u32 v38, s15, v141, v38
	v_ashrrev_i32_e32 v39, 31, v38
	v_lshlrev_b64 v[38:39], 11, v[38:39]
	v_lshl_add_u64 v[38:39], v[36:37], 0, v[38:39]
	s_waitcnt lgkmcnt(0)
	global_store_dwordx4 v[38:39], v[104:107], off
	s_mul_i32 s0, s10, s54
	s_add_i32 s18, s0, s7
	s_cmpk_lt_i32 s11, 0x480
	s_cbranch_scc0 .LBB0_343

.LBB0_338:
	s_add_i32 s19, s18, s54
	v_add_u32_e32 v32, v126, v124
	s_cmpk_gt_i32 s19, 0x47f
	s_waitcnt lgkmcnt(0)
	s_barrier
	s_waitcnt vmcnt(8)
	ds_write_b128 v32, v[4:7] offset:34816
	ds_write_b128 v143, v[0:3] offset:33792
	ds_write_b128 v32, v[12:15] offset:34944
	ds_write_b128 v143, v[8:11] offset:33920
	ds_write_b128 v32, v[20:23] offset:35072
	ds_write_b128 v143, v[16:19] offset:34048
	ds_write_b128 v32, v[28:31] offset:35200
	ds_write_b128 v143, v[24:27] offset:34176
	s_waitcnt lgkmcnt(0)
	s_barrier
	s_cbranch_scc1 .LBB0_332
	s_lshl_b32 s21, s19, 5
	s_cmpk_gt_i32 s19, 0x3ff
	s_mov_b64 s[0:1], -1
	s_cbranch_scc0 .LBB0_341
	s_and_b32 s0, s21, 0x7fffff00
	s_add_i32 s20, s0, 0xffff8000
	s_mov_b64 s[0:1], 0

.LBB0_398:
	v_ashrrev_i32_e32 v66, 3, v32
	v_readlane_b32 s0, v254, 21
	v_and_b32_e32 v34, 56, v33
	v_lshlrev_b32_e32 v208, 1, v34
	v_add_u32_e32 v0, s0, v66
	v_add_u32_e32 v2, 0xc0, v0
	v_ashrrev_i32_e32 v3, 31, v2
	v_readlane_b32 s0, v254, 33
	v_lshlrev_b64 v[2:3], 11, v[2:3]
	v_readlane_b32 s1, v254, 34
	s_waitcnt vmcnt(0)
	v_ashrrev_i32_e32 v1, 31, v0
	v_and_b32_e32 v33, 24, v33
	v_lshl_add_u64 v[2:3], s[0:1], 0, v[2:3]
	v_lshl_add_u64 v[2:3], v[2:3], 0, v[208:209]
	global_load_dwordx4 v[24:27], v[2:3], off offset:1024
	global_load_dwordx4 v[28:31], v[2:3], off
	v_add_u32_e32 v2, 0x80, v0
	v_ashrrev_i32_e32 v3, 31, v2
	v_lshlrev_b64 v[2:3], 11, v[2:3]
	v_lshl_add_u64 v[2:3], s[0:1], 0, v[2:3]
	v_lshl_add_u64 v[2:3], v[2:3], 0, v[208:209]
	global_load_dwordx4 v[16:19], v[2:3], off offset:1024
	global_load_dwordx4 v[20:23], v[2:3], off
	v_add_u32_e32 v2, 64, v0
	v_ashrrev_i32_e32 v3, 31, v2
	v_lshlrev_b64 v[2:3], 11, v[2:3]
	v_lshlrev_b64 v[0:1], 11, v[0:1]
	v_lshl_add_u64 v[2:3], s[0:1], 0, v[2:3]
	v_lshl_add_u64 v[0:1], s[0:1], 0, v[0:1]
	v_lshl_add_u64 v[2:3], v[2:3], 0, v[208:209]
	v_lshl_add_u64 v[4:5], v[0:1], 0, v[208:209]
	global_load_dwordx4 v[8:11], v[2:3], off offset:1024
	global_load_dwordx4 v[12:15], v[2:3], off
	s_nop 0
	global_load_dwordx4 v[0:3], v[4:5], off offset:1024
	s_nop 0
	global_load_dwordx4 v[4:7], v[4:5], off
	s_and_b32 s0, s16, 0xffffffc0
	s_add_i32 s0, s0, 0
	v_add_u32_e32 v33, s0, v33
	s_lshr_b32 s0, s16, 1
	v_bfe_u32 v37, v32, 4, 2
	v_bfe_u32 v38, v32, 2, 2
	s_and_b32 s0, s0, 0xfffffc0
	v_lshl_or_b32 v38, v37, 3, v38
	v_lshlrev_b32_e32 v68, 4, v37
	v_lshl_or_b32 v37, v37, 2, s0
	s_lshl_b32 s0, s16, 1
	s_and_b32 s0, s0, 0x80
	v_and_b32_e32 v35, 15, v32
	s_add_i32 s0, s0, 0
	v_lshl_add_u32 v39, v35, 2, s0
	s_movk_i32 s0, 0x210
	v_mov_b32_e32 v43, 0x8400
	v_mov_b32_e32 v44, 0xc600
	v_mul_lo_u32 v41, v66, s0
	v_mul_u32_u24_e32 v42, 0x210, v38
	v_mad_u32_u24 v43, v38, s0, v43
	v_mad_u32_u24 v38, v38, s0, v44
	s_movk_i32 s0, 0x110
	v_mul_u32_u24_e32 v70, 0x110, v35
	v_mul_lo_u32 v35, v37, s0
	v_ashrrev_i32_e32 v37, 9, v32
	v_and_b32_e32 v44, 63, v66
	v_bfe_u32 v45, v66, 2, 4
	v_lshlrev_b32_e32 v46, 6, v66
	v_lshl_or_b32 v45, v37, 4, v45
	v_and_b32_e32 v46, 0xc0, v46
	v_lshl_add_u32 v72, v44, 6, v37
	v_add_u32_e32 v44, 0x200, v32
	v_add_u32_e32 v71, v45, v46
	v_ashrrev_i32_e32 v45, 3, v44
	v_ashrrev_i32_e32 v44, 9, v44
	v_and_b32_e32 v46, 63, v45
	v_bfe_u32 v47, v45, 2, 4
	v_lshl_or_b32 v47, v44, 4, v47
	v_lshlrev_b32_e32 v48, 6, v45
	v_lshl_add_u32 v74, v46, 6, v44
	v_mul_lo_u32 v44, v45, s0
	v_add_u32_e32 v45, 0x400, v32
	v_and_b32_e32 v48, 0xc0, v48
	v_ashrrev_i32_e32 v46, 3, v45
	v_and_b32_e32 v36, 7, v32
	v_add_u32_e32 v73, v47, v48
	v_ashrrev_i32_e32 v45, 9, v45
	v_and_b32_e32 v47, 63, v46
	v_bfe_u32 v48, v46, 2, 4
	v_lshlrev_b32_e32 v49, 6, v46
	v_add_u32_e32 v32, 0x600, v32
	v_lshl_or_b32 v48, v45, 4, v48
	v_and_b32_e32 v49, 0xc0, v49
	v_lshl_add_u32 v76, v47, 6, v45
	v_mul_lo_u32 v45, v46, s0
	v_ashrrev_i32_e32 v46, 3, v32
	v_add_u32_e32 v69, 0, v41
	v_add_u32_e32 v75, v48, v49
	v_ashrrev_i32_e32 v32, 9, v32
	v_and_b32_e32 v47, 63, v46
	v_bfe_u32 v48, v46, 2, 4
	v_lshlrev_b32_e32 v49, 6, v46
	v_lshlrev_b32_e32 v67, 4, v36
	v_lshlrev_b32_e32 v36, 3, v36
	v_lshl_add_u32 v40, v34, 2, 0
	v_add_u32_e32 v41, 0x8800, v69
	v_mul_lo_u32 v37, v66, s0
	v_lshl_or_b32 v48, v32, 4, v48
	v_and_b32_e32 v49, 0xc0, v49
	v_lshl_add_u32 v78, v47, 6, v32
	v_mul_lo_u32 v32, v46, s0
	v_add_u32_e32 v77, v48, v49
	s_mov_b32 s17, 0
	v_add_u32_e32 v79, v41, v67
	v_lshlrev_b32_e32 v208, 1, v36
	v_add_u32_e32 v80, v33, v42
	v_add_u32_e32 v81, v33, v43
	v_add_u32_e32 v82, v33, v38
	v_add_u32_e32 v83, v39, v35
	v_add_u32_e32 v84, v40, v37
	v_lshlrev_b32_e32 v64, 1, v34
	v_add_u32_e32 v85, v40, v44
	v_add_u32_e32 v86, v40, v45
	v_add_u32_e32 v87, v40, v32
	s_mov_b32 s16, s7
	s_waitcnt vmcnt(0)
	s_branch .LBB0_401
.LBB0_399:
	v_add_u32_e32 v24, s0, v66
	v_ashrrev_i32_e32 v25, 31, v24
	v_lshlrev_b64 v[0:1], 11, v[24:25]
	v_add_u32_e32 v8, 64, v24
	v_add_u32_e32 v16, 0x80, v24
	v_add_u32_e32 v24, 0xc0, v24
	v_readlane_b32 s4, v254, 31
	v_ashrrev_i32_e32 v9, 31, v8
	v_ashrrev_i32_e32 v17, 31, v16
	v_ashrrev_i32_e32 v25, 31, v24
	v_readlane_b32 s5, v254, 32
	s_lshl_b32 s0, s24, 7
	v_lshlrev_b64 v[8:9], 11, v[8:9]
	v_lshlrev_b64 v[16:17], 11, v[16:17]
	v_lshlrev_b64 v[24:25], 11, v[24:25]
	v_lshl_add_u64 v[0:1], s[4:5], 0, v[0:1]
	s_and_b32 s36, s0, 0x380
	v_lshl_add_u64 v[8:9], s[4:5], 0, v[8:9]
	v_lshl_add_u64 v[16:17], s[4:5], 0, v[16:17]
	v_lshl_add_u64 v[24:25], s[4:5], 0, v[24:25]
	v_lshl_add_u64 v[0:1], v[0:1], 0, s[36:37]
	v_lshl_add_u64 v[8:9], v[8:9], 0, s[36:37]
	v_lshl_add_u64 v[16:17], v[16:17], 0, s[36:37]
	v_lshl_add_u64 v[24:25], v[24:25], 0, s[36:37]
	v_lshl_add_u64 v[0:1], v[0:1], 0, v[208:209]
	v_lshl_add_u64 v[8:9], v[8:9], 0, v[208:209]
	v_lshl_add_u64 v[16:17], v[16:17], 0, v[208:209]
	v_lshl_add_u64 v[24:25], v[24:25], 0, v[208:209]
	s_add_i32 s18, s20, s21
	s_lshl_b32 s19, s21, 6
	s_sub_i32 s18, s18, s19
	s_lshl_b32 s10, s16, 7
	s_and_b32 s10, s10, 0x380
	s_add_i32 s10, s10, 0xc100000
	s_mov_b32 s11, 0
	v_mov_b32_e32 v140, v64
	v_mov_b32_e32 v141, 0
	v_add_u32_e32 v132, s18, v72
	v_add_u32_e32 v133, s20, v71
	v_cndmask_b32_e64 v132, v133, v132, s[42:43]
	v_ashrrev_i32_e32 v133, 31, v132
	v_lshlrev_b64 v[132:133], 11, v[132:133]
	v_lshl_add_u64 v[132:133], s[60:61], 0, v[132:133]
	v_lshl_add_u64 v[132:133], v[132:133], 0, s[10:11]
	v_lshl_add_u64 v[132:133], v[132:133], 0, v[140:141]
	v_add_u32_e32 v134, s18, v74
	v_add_u32_e32 v135, s20, v73
	v_cndmask_b32_e64 v134, v135, v134, s[42:43]
	v_ashrrev_i32_e32 v135, 31, v134
	v_lshlrev_b64 v[134:135], 11, v[134:135]
	v_lshl_add_u64 v[134:135], s[60:61], 0, v[134:135]
	v_lshl_add_u64 v[134:135], v[134:135], 0, s[10:11]
	v_lshl_add_u64 v[134:135], v[134:135], 0, v[140:141]
	v_add_u32_e32 v136, s18, v76
	v_add_u32_e32 v137, s20, v75
	v_cndmask_b32_e64 v136, v137, v136, s[42:43]
	v_ashrrev_i32_e32 v137, 31, v136
	v_lshlrev_b64 v[136:137], 11, v[136:137]
	v_lshl_add_u64 v[136:137], s[60:61], 0, v[136:137]
	v_lshl_add_u64 v[136:137], v[136:137], 0, s[10:11]
	v_lshl_add_u64 v[136:137], v[136:137], 0, v[140:141]
	v_add_u32_e32 v138, s18, v78
	v_add_u32_e32 v139, s20, v77
	v_cndmask_b32_e64 v138, v139, v138, s[42:43]
	v_ashrrev_i32_e32 v139, 31, v138
	v_lshlrev_b64 v[138:139], 11, v[138:139]
	v_lshl_add_u64 v[138:139], s[60:61], 0, v[138:139]
	v_lshl_add_u64 v[138:139], v[138:139], 0, s[10:11]
	v_lshl_add_u64 v[138:139], v[138:139], 0, v[140:141]
	s_and_b64 s[0:1], s[42:43], exec
	v_readlane_b32 s0, v254, 46
	s_cselect_b32 s0, 0, s0
	ds_read_b64_tr_b16 v[58:59], v80 offset:36928
	ds_read_b64_tr_b16 v[56:57], v80 offset:34816
	ds_read_b64_tr_b16 v[60:61], v80 offset:34848
	ds_read_b64_tr_b16 v[48:49], v80 offset:51712
	ds_read_b64_tr_b16 v[50:51], v80 offset:53824
	ds_read_b64_tr_b16 v[42:43], v81 offset:36928
	ds_read_b64_tr_b16 v[40:41], v81 offset:34816
	ds_read_b64_tr_b16 v[44:45], v81 offset:34848
	ds_read_b64_tr_b16 v[34:35], v82 offset:36928
	ds_read_b64_tr_b16 v[32:33], v82 offset:34816
	ds_read_b64_tr_b16 v[36:37], v82 offset:34848
	ds_read_b64_tr_b16 v[62:63], v80 offset:36960
	ds_read_b64_tr_b16 v[52:53], v80 offset:51744
	ds_read_b64_tr_b16 v[54:55], v80 offset:53856
	ds_read_b64_tr_b16 v[46:47], v81 offset:36960
	ds_read_b64_tr_b16 v[38:39], v82 offset:36960
	v_add3_u32 v65, s0, v68, v70
	s_add_i32 s0, s20, s21
	s_lshl_b32 s1, s21, 6
	s_sub_i32 s0, s0, s1
	s_lshl_b32 s1, s16, 7
	s_and_b32 s36, s1, 0x380
	s_mov_b32 s1, 0xc100000
	s_add_i32 s17, s17, 1
	ds_read_b128 v[144:147], v65
	ds_read_b128 v[148:151], v65 offset:64
	ds_read_b128 v[152:155], v65 offset:128
	ds_read_b128 v[156:159], v65 offset:192
	ds_read_b128 v[160:163], v65 offset:4352
	ds_read_b128 v[164:167], v65 offset:4416
	s_waitcnt lgkmcnt(5)
	v_mfma_f32_16x16x32_bf16 v[92:95], v[144:147], v[56:59], 0
	v_mfma_f32_16x16x32_bf16 v[88:91], v[144:147], v[60:63], 0
	ds_read_b128 v[144:147], v65 offset:4480
	s_waitcnt lgkmcnt(5)
	v_mfma_f32_16x16x32_bf16 v[92:95], v[148:151], v[48:51], v[92:95]
	v_mfma_f32_16x16x32_bf16 v[88:91], v[148:151], v[52:55], v[88:91]
	ds_read_b128 v[148:151], v65 offset:4544
	s_waitcnt lgkmcnt(5)
	v_mfma_f32_16x16x32_bf16 v[92:95], v[152:155], v[40:43], v[92:95]
	v_mfma_f32_16x16x32_bf16 v[88:91], v[152:155], v[44:47], v[88:91]
	ds_read_b128 v[152:155], v65 offset:8704
	s_waitcnt lgkmcnt(5)
	v_mfma_f32_16x16x32_bf16 v[92:95], v[156:159], v[32:35], v[92:95]
	v_mfma_f32_16x16x32_bf16 v[88:91], v[156:159], v[36:39], v[88:91]
	ds_read_b128 v[156:159], v65 offset:8768
	global_load_dwordx4 v[116:119], v[132:133], off offset:1024
	s_waitcnt lgkmcnt(5)
	v_mfma_f32_16x16x32_bf16 v[100:103], v[160:163], v[56:59], 0
	v_mfma_f32_16x16x32_bf16 v[96:99], v[160:163], v[60:63], 0
	ds_read_b128 v[160:163], v65 offset:8832
	s_waitcnt lgkmcnt(5)
	v_mfma_f32_16x16x32_bf16 v[100:103], v[164:167], v[48:51], v[100:103]
	v_mfma_f32_16x16x32_bf16 v[96:99], v[164:167], v[52:55], v[96:99]
	ds_read_b128 v[164:167], v65 offset:8896
	s_waitcnt lgkmcnt(5)
	v_mfma_f32_16x16x32_bf16 v[100:103], v[144:147], v[40:43], v[100:103]
	v_mfma_f32_16x16x32_bf16 v[96:99], v[144:147], v[44:47], v[96:99]
	ds_read_b128 v[144:147], v65 offset:13056
	s_waitcnt lgkmcnt(5)
	v_mfma_f32_16x16x32_bf16 v[100:103], v[148:151], v[32:35], v[100:103]
	v_mfma_f32_16x16x32_bf16 v[96:99], v[148:151], v[36:39], v[96:99]
	ds_read_b128 v[148:151], v65 offset:13120
	global_load_dwordx4 v[120:123], v[134:135], off offset:1024
	s_waitcnt lgkmcnt(5)
	v_mfma_f32_16x16x32_bf16 v[108:111], v[152:155], v[56:59], 0
	v_mfma_f32_16x16x32_bf16 v[104:107], v[152:155], v[60:63], 0
	ds_read_b128 v[152:155], v65 offset:13184
	s_waitcnt lgkmcnt(5)
	v_mfma_f32_16x16x32_bf16 v[108:111], v[156:159], v[48:51], v[108:111]
	v_mfma_f32_16x16x32_bf16 v[104:107], v[156:159], v[52:55], v[104:107]
	ds_read_b128 v[156:159], v65 offset:13248
	s_waitcnt lgkmcnt(5)
	v_mfma_f32_16x16x32_bf16 v[108:111], v[160:163], v[40:43], v[108:111]
	v_mfma_f32_16x16x32_bf16 v[104:107], v[160:163], v[44:47], v[104:107]
	s_waitcnt lgkmcnt(4)
	v_mfma_f32_16x16x32_bf16 v[108:111], v[164:167], v[32:35], v[108:111]
	v_mfma_f32_16x16x32_bf16 v[104:107], v[164:167], v[36:39], v[104:107]
	global_load_dwordx4 v[124:127], v[136:137], off offset:1024
	s_waitcnt lgkmcnt(3)
	v_mfma_f32_16x16x32_bf16 v[56:59], v[144:147], v[56:59], 0
	v_mfma_f32_16x16x32_bf16 v[60:63], v[144:147], v[60:63], 0
	s_waitcnt lgkmcnt(2)
	v_mfma_f32_16x16x32_bf16 v[48:51], v[148:151], v[48:51], v[56:59]
	v_mfma_f32_16x16x32_bf16 v[52:55], v[148:151], v[52:55], v[60:63]
	s_waitcnt lgkmcnt(1)
	v_mfma_f32_16x16x32_bf16 v[40:43], v[152:155], v[40:43], v[48:51]
	v_mfma_f32_16x16x32_bf16 v[44:47], v[152:155], v[44:47], v[52:55]
	s_waitcnt lgkmcnt(0)
	s_barrier
	v_mfma_f32_16x16x32_bf16 v[32:35], v[156:159], v[32:35], v[40:43]
	v_mfma_f32_16x16x32_bf16 v[36:39], v[156:159], v[36:39], v[44:47]
	global_load_dwordx4 v[128:131], v[138:139], off offset:1024
	s_branch .Lfftb_stage
.LBB0_400:
	s_add_i32 s18, s20, s21
	s_lshl_b32 s19, s21, 6
	s_sub_i32 s18, s18, s19
	s_lshl_b32 s10, s16, 7
	s_and_b32 s10, s10, 0x380
	s_add_i32 s10, s10, 0xc100000
	s_mov_b32 s11, 0
	v_mov_b32_e32 v140, v64
	v_mov_b32_e32 v141, 0
	v_add_u32_e32 v132, s18, v72
	v_add_u32_e32 v133, s20, v71
	v_cndmask_b32_e64 v132, v133, v132, s[42:43]
	v_ashrrev_i32_e32 v133, 31, v132
	v_lshlrev_b64 v[132:133], 11, v[132:133]
	v_lshl_add_u64 v[132:133], s[60:61], 0, v[132:133]
	v_lshl_add_u64 v[132:133], v[132:133], 0, s[10:11]
	v_lshl_add_u64 v[132:133], v[132:133], 0, v[140:141]
	v_add_u32_e32 v134, s18, v74
	v_add_u32_e32 v135, s20, v73
	v_cndmask_b32_e64 v134, v135, v134, s[42:43]
	v_ashrrev_i32_e32 v135, 31, v134
	v_lshlrev_b64 v[134:135], 11, v[134:135]
	v_lshl_add_u64 v[134:135], s[60:61], 0, v[134:135]
	v_lshl_add_u64 v[134:135], v[134:135], 0, s[10:11]
	v_lshl_add_u64 v[134:135], v[134:135], 0, v[140:141]
	v_add_u32_e32 v136, s18, v76
	v_add_u32_e32 v137, s20, v75
	v_cndmask_b32_e64 v136, v137, v136, s[42:43]
	v_ashrrev_i32_e32 v137, 31, v136
	v_lshlrev_b64 v[136:137], 11, v[136:137]
	v_lshl_add_u64 v[136:137], s[60:61], 0, v[136:137]
	v_lshl_add_u64 v[136:137], v[136:137], 0, s[10:11]
	v_lshl_add_u64 v[136:137], v[136:137], 0, v[140:141]
	v_add_u32_e32 v138, s18, v78
	v_add_u32_e32 v139, s20, v77
	v_cndmask_b32_e64 v138, v139, v138, s[42:43]
	v_ashrrev_i32_e32 v139, 31, v138
	v_lshlrev_b64 v[138:139], 11, v[138:139]
	v_lshl_add_u64 v[138:139], s[60:61], 0, v[138:139]
	v_lshl_add_u64 v[138:139], v[138:139], 0, s[10:11]
	v_lshl_add_u64 v[138:139], v[138:139], 0, v[140:141]
	s_and_b64 s[0:1], s[42:43], exec
	v_readlane_b32 s0, v254, 46
	s_cselect_b32 s0, 0, s0
	ds_read_b64_tr_b16 v[58:59], v80 offset:36928
	ds_read_b64_tr_b16 v[56:57], v80 offset:34816
	ds_read_b64_tr_b16 v[60:61], v80 offset:34848
	ds_read_b64_tr_b16 v[48:49], v80 offset:51712
	ds_read_b64_tr_b16 v[50:51], v80 offset:53824
	ds_read_b64_tr_b16 v[42:43], v81 offset:36928
	ds_read_b64_tr_b16 v[40:41], v81 offset:34816
	ds_read_b64_tr_b16 v[44:45], v81 offset:34848
	ds_read_b64_tr_b16 v[34:35], v82 offset:36928
	ds_read_b64_tr_b16 v[32:33], v82 offset:34816
	ds_read_b64_tr_b16 v[36:37], v82 offset:34848
	ds_read_b64_tr_b16 v[62:63], v80 offset:36960
	ds_read_b64_tr_b16 v[52:53], v80 offset:51744
	ds_read_b64_tr_b16 v[54:55], v80 offset:53856
	ds_read_b64_tr_b16 v[46:47], v81 offset:36960
	ds_read_b64_tr_b16 v[38:39], v82 offset:36960
	v_add3_u32 v65, s0, v68, v70
	v_mov_b32_e32 v0, v132
	v_mov_b32_e32 v1, v133
	v_mov_b32_e32 v8, v132
	v_mov_b32_e32 v9, v133
	v_mov_b32_e32 v16, v132
	v_mov_b32_e32 v17, v133
	v_mov_b32_e32 v24, v132
	v_mov_b32_e32 v25, v133
	s_add_i32 s0, s20, s21
	s_lshl_b32 s1, s21, 6
	s_sub_i32 s0, s0, s1
	s_lshl_b32 s1, s16, 7
	s_and_b32 s36, s1, 0x380
	s_mov_b32 s1, 0xc100000
	s_add_i32 s17, s17, 1
	ds_read_b128 v[144:147], v65
	ds_read_b128 v[148:151], v65 offset:64
	ds_read_b128 v[152:155], v65 offset:128
	ds_read_b128 v[156:159], v65 offset:192
	ds_read_b128 v[160:163], v65 offset:4352
	ds_read_b128 v[164:167], v65 offset:4416
	s_waitcnt lgkmcnt(5)
	v_mfma_f32_16x16x32_bf16 v[92:95], v[144:147], v[56:59], 0
	v_mfma_f32_16x16x32_bf16 v[88:91], v[144:147], v[60:63], 0
	ds_read_b128 v[144:147], v65 offset:4480
	s_waitcnt lgkmcnt(5)
	v_mfma_f32_16x16x32_bf16 v[92:95], v[148:151], v[48:51], v[92:95]
	v_mfma_f32_16x16x32_bf16 v[88:91], v[148:151], v[52:55], v[88:91]
	ds_read_b128 v[148:151], v65 offset:4544
	s_waitcnt lgkmcnt(5)
	v_mfma_f32_16x16x32_bf16 v[92:95], v[152:155], v[40:43], v[92:95]
	v_mfma_f32_16x16x32_bf16 v[88:91], v[152:155], v[44:47], v[88:91]
	ds_read_b128 v[152:155], v65 offset:8704
	s_waitcnt lgkmcnt(5)
	v_mfma_f32_16x16x32_bf16 v[92:95], v[156:159], v[32:35], v[92:95]
	v_mfma_f32_16x16x32_bf16 v[88:91], v[156:159], v[36:39], v[88:91]
	ds_read_b128 v[156:159], v65 offset:8768
	global_load_dwordx4 v[116:119], v[132:133], off offset:1024
	s_waitcnt lgkmcnt(5)
	v_mfma_f32_16x16x32_bf16 v[100:103], v[160:163], v[56:59], 0
	v_mfma_f32_16x16x32_bf16 v[96:99], v[160:163], v[60:63], 0
	ds_read_b128 v[160:163], v65 offset:8832
	s_waitcnt lgkmcnt(5)
	v_mfma_f32_16x16x32_bf16 v[100:103], v[164:167], v[48:51], v[100:103]
	v_mfma_f32_16x16x32_bf16 v[96:99], v[164:167], v[52:55], v[96:99]
	ds_read_b128 v[164:167], v65 offset:8896
	s_waitcnt lgkmcnt(5)
	v_mfma_f32_16x16x32_bf16 v[100:103], v[144:147], v[40:43], v[100:103]
	v_mfma_f32_16x16x32_bf16 v[96:99], v[144:147], v[44:47], v[96:99]
	ds_read_b128 v[144:147], v65 offset:13056
	s_waitcnt lgkmcnt(5)
	v_mfma_f32_16x16x32_bf16 v[100:103], v[148:151], v[32:35], v[100:103]
	v_mfma_f32_16x16x32_bf16 v[96:99], v[148:151], v[36:39], v[96:99]
	ds_read_b128 v[148:151], v65 offset:13120
	global_load_dwordx4 v[120:123], v[134:135], off offset:1024
	s_waitcnt lgkmcnt(5)
	v_mfma_f32_16x16x32_bf16 v[108:111], v[152:155], v[56:59], 0
	v_mfma_f32_16x16x32_bf16 v[104:107], v[152:155], v[60:63], 0
	ds_read_b128 v[152:155], v65 offset:13184
	s_waitcnt lgkmcnt(5)
	v_mfma_f32_16x16x32_bf16 v[108:111], v[156:159], v[48:51], v[108:111]
	v_mfma_f32_16x16x32_bf16 v[104:107], v[156:159], v[52:55], v[104:107]
	ds_read_b128 v[156:159], v65 offset:13248
	s_waitcnt lgkmcnt(5)
	v_mfma_f32_16x16x32_bf16 v[108:111], v[160:163], v[40:43], v[108:111]
	v_mfma_f32_16x16x32_bf16 v[104:107], v[160:163], v[44:47], v[104:107]
	s_waitcnt lgkmcnt(4)
	v_mfma_f32_16x16x32_bf16 v[108:111], v[164:167], v[32:35], v[108:111]
	v_mfma_f32_16x16x32_bf16 v[104:107], v[164:167], v[36:39], v[104:107]
	global_load_dwordx4 v[124:127], v[136:137], off offset:1024
	s_waitcnt lgkmcnt(3)
	v_mfma_f32_16x16x32_bf16 v[56:59], v[144:147], v[56:59], 0
	v_mfma_f32_16x16x32_bf16 v[60:63], v[144:147], v[60:63], 0
	s_waitcnt lgkmcnt(2)
	v_mfma_f32_16x16x32_bf16 v[48:51], v[148:151], v[48:51], v[56:59]
	v_mfma_f32_16x16x32_bf16 v[52:55], v[148:151], v[52:55], v[60:63]
	s_waitcnt lgkmcnt(1)
	v_mfma_f32_16x16x32_bf16 v[40:43], v[152:155], v[40:43], v[48:51]
	v_mfma_f32_16x16x32_bf16 v[44:47], v[152:155], v[44:47], v[52:55]
	s_waitcnt lgkmcnt(0)
	s_barrier
	v_mfma_f32_16x16x32_bf16 v[32:35], v[156:159], v[32:35], v[40:43]
	v_mfma_f32_16x16x32_bf16 v[36:39], v[156:159], v[36:39], v[44:47]
	global_load_dwordx4 v[128:131], v[138:139], off offset:1024
.Lfftb_stage:
	s_nop 7
	v_cndmask_b32_e64 v40, v236, v237, s[42:43]
	v_mul_f32_e32 v41, v40, v92
	v_mul_f32_e32 v42, v40, v88
	v_add_u32_e32 v43, 0x8800, v83
	ds_write2_b32 v43, v41, v42 offset1:16
	global_load_dwordx4 v[4:7], v[0:1], off
	v_mul_f32_e32 v41, v40, v93
	v_mul_f32_e32 v42, v40, v89
	ds_write2_b32 v43, v41, v42 offset0:68 offset1:84
	v_mul_f32_e32 v41, v40, v94
	v_mul_f32_e32 v42, v40, v90
	ds_write2_b32 v43, v41, v42 offset0:136 offset1:152
	v_mul_f32_e32 v41, v40, v95
	v_mul_f32_e32 v42, v40, v91
	global_load_dwordx4 v[0:3], v[0:1], off offset:1024
	ds_write2_b32 v43, v41, v42 offset0:204 offset1:220
	v_mul_f32_e32 v41, v40, v100
	v_mul_f32_e32 v42, v40, v96
	v_add_u32_e32 v43, 0x9800, v83
	ds_write2_b32 v43, v41, v42 offset0:64 offset1:80
	v_mul_f32_e32 v41, v40, v101
	v_mul_f32_e32 v42, v40, v97
	ds_write2_b32 v43, v41, v42 offset0:132 offset1:148
	global_load_dwordx4 v[12:15], v[8:9], off
	v_mul_f32_e32 v41, v40, v102
	v_mul_f32_e32 v42, v40, v98
	ds_write2_b32 v43, v41, v42 offset0:200 offset1:216
	v_mul_f32_e32 v41, v40, v103
	v_mul_f32_e32 v42, v40, v99
	v_add_u32_e32 v43, 0x9c00, v83
	ds_write2_b32 v43, v41, v42 offset0:12 offset1:28
	v_mul_f32_e32 v41, v40, v108
	global_load_dwordx4 v[8:11], v[8:9], off offset:1024
	v_mul_f32_e32 v42, v40, v104
	v_add_u32_e32 v43, 0xa800, v83
	ds_write2_b32 v43, v41, v42 offset0:128 offset1:144
	v_mul_f32_e32 v41, v40, v109
	v_mul_f32_e32 v42, v40, v105
	ds_write2_b32 v43, v41, v42 offset0:196 offset1:212
	v_mul_f32_e32 v41, v40, v110
	v_mul_f32_e32 v42, v40, v106
	global_load_dwordx4 v[20:23], v[16:17], off
	v_add_u32_e32 v43, 0xac00, v83
	ds_write2_b32 v43, v41, v42 offset0:8 offset1:24
	v_mul_f32_e32 v41, v40, v111
	v_mul_f32_e32 v42, v40, v107
	ds_write2_b32 v43, v41, v42 offset0:76 offset1:92
	v_mul_f32_e32 v32, v40, v32
	v_mul_f32_e32 v36, v40, v36
	v_add_u32_e32 v41, 0xb800, v83
	global_load_dwordx4 v[16:19], v[16:17], off offset:1024
	ds_write2_b32 v41, v32, v36 offset0:192 offset1:208
	v_mul_f32_e32 v32, v40, v33
	v_mul_f32_e32 v33, v40, v37
	v_add_u32_e32 v36, 0xbc00, v83
	ds_write2_b32 v36, v32, v33 offset0:4 offset1:20
	v_mul_f32_e32 v32, v40, v34
	v_mul_f32_e32 v33, v40, v38
	ds_write2_b32 v36, v32, v33 offset0:72 offset1:88
	global_load_dwordx4 v[28:31], v[24:25], off
	v_mul_f32_e32 v32, v40, v35
	v_mul_f32_e32 v33, v40, v39
	ds_write2_b32 v36, v32, v33 offset0:140 offset1:156
	global_load_dwordx4 v[24:27], v[24:25], off offset:1024
	v_add_u32_e32 v32, s0, v72
	v_add_u32_e32 v33, s20, v71
	v_cndmask_b32_e64 v40, v33, v32, s[42:43]
	v_ashrrev_i32_e32 v41, 31, v40
	v_lshlrev_b64 v[40:41], 11, v[40:41]
	v_lshl_add_u64 v[40:41], s[60:61], 0, v[40:41]
	v_lshl_add_u64 v[40:41], v[40:41], 0, s[36:37]
	v_mov_b32_e32 v65, v209
	v_lshl_add_u64 v[40:41], v[40:41], 0, v[64:65]
	v_add_co_u32_e32 v44, vcc, s1, v40
	s_waitcnt lgkmcnt(0)
	s_nop 0
	v_addc_co_u32_e32 v45, vcc, 0, v41, vcc
	s_barrier
	ds_read_b128 v[32:35], v84 offset:34816
	ds_read_b128 v[36:39], v84 offset:34832
	s_waitcnt lgkmcnt(1)
	v_mov_b32_e32 v49, v34
	v_mov_b32_e32 v34, v33
	v_mov_b32_e32 v48, v32
	s_waitcnt vmcnt(11)
	v_mov_b32_e32 v40, v116
	v_mov_b32_e32 v41, v117
	v_mov_b32_e32 v42, v118
	v_mov_b32_e32 v43, v119
	v_lshlrev_b32_e32 v47, 16, v41
	v_lshlrev_b32_e32 v46, 16, v40
	v_and_b32_e32 v41, 0xffff0000, v41
	v_and_b32_e32 v40, 0xffff0000, v40
	v_pk_mul_f32 v[32:33], v[34:35], v[40:41]
	v_lshlrev_b32_e32 v35, 16, v43
	v_lshlrev_b32_e32 v34, 16, v42
	s_waitcnt lgkmcnt(0)
	v_mov_b32_e32 v40, v36
	v_mov_b32_e32 v41, v38
	v_pk_mul_f32 v[34:35], v[40:41], v[34:35]
	v_and_b32_e32 v41, 0xffff0000, v43
	v_and_b32_e32 v40, 0xffff0000, v42
	v_mov_b32_e32 v38, v37
	v_pk_mul_f32 v[36:37], v[38:39], v[40:41]
	v_pk_mul_f32 v[46:47], v[48:49], v[46:47]
	v_bfe_u32 v38, v37, 16, 1
	v_bfe_u32 v39, v36, 16, 1
	v_bfe_u32 v40, v33, 16, 1
	v_bfe_u32 v41, v32, 16, 1
	v_add3_u32 v32, v32, v41, s3
	v_add3_u32 v33, v33, v40, s3
	v_add3_u32 v36, v36, v39, s3
	v_add3_u32 v37, v37, v38, s3
	v_bfe_u32 v38, v46, 16, 1
	v_bfe_u32 v39, v47, 16, 1
	v_bfe_u32 v40, v34, 16, 1
	v_bfe_u32 v41, v35, 16, 1
	v_add3_u32 v35, v35, v41, s3
	v_add3_u32 v34, v34, v40, s3
	v_add3_u32 v39, v47, v39, s3
	v_add3_u32 v38, v46, v38, s3
	v_lshrrev_b32_e32 v38, 16, v38
	v_lshrrev_b32_e32 v39, 16, v39
	v_lshrrev_b32_e32 v34, 16, v34
	v_lshrrev_b32_e32 v35, 16, v35
	v_and_or_b32 v35, v37, s23, v35
	v_and_or_b32 v34, v36, s23, v34
	v_and_or_b32 v33, v33, s23, v39
	v_and_or_b32 v32, v32, s23, v38
	global_store_dwordx4 v[44:45], v[32:35], off offset:1024
	s_nop 1
	v_add_u32_e32 v32, s0, v74
	v_add_u32_e32 v33, s20, v73
	v_cndmask_b32_e64 v40, v33, v32, s[42:43]
	v_ashrrev_i32_e32 v41, 31, v40
	v_lshlrev_b64 v[40:41], 11, v[40:41]
	v_lshl_add_u64 v[40:41], s[60:61], 0, v[40:41]
	v_lshl_add_u64 v[40:41], v[40:41], 0, s[36:37]
	v_lshl_add_u64 v[40:41], v[40:41], 0, v[64:65]
	v_add_co_u32_e32 v44, vcc, s1, v40
	ds_read_b128 v[32:35], v85 offset:34816
	ds_read_b128 v[36:39], v85 offset:34832
	v_addc_co_u32_e32 v45, vcc, 0, v41, vcc
	s_waitcnt lgkmcnt(1)
	v_mov_b32_e32 v49, v34
	v_mov_b32_e32 v34, v33
	v_mov_b32_e32 v48, v32
	s_waitcnt vmcnt(11)
	v_mov_b32_e32 v40, v120
	v_mov_b32_e32 v41, v121
	v_mov_b32_e32 v42, v122
	v_mov_b32_e32 v43, v123
	v_lshlrev_b32_e32 v47, 16, v41
	v_lshlrev_b32_e32 v46, 16, v40
	v_and_b32_e32 v41, 0xffff0000, v41
	v_and_b32_e32 v40, 0xffff0000, v40
	v_pk_mul_f32 v[32:33], v[34:35], v[40:41]
	v_lshlrev_b32_e32 v35, 16, v43
	v_lshlrev_b32_e32 v34, 16, v42
	s_waitcnt lgkmcnt(0)
	v_mov_b32_e32 v40, v36
	v_mov_b32_e32 v41, v38
	v_pk_mul_f32 v[34:35], v[40:41], v[34:35]
	v_and_b32_e32 v41, 0xffff0000, v43
	v_and_b32_e32 v40, 0xffff0000, v42
	v_mov_b32_e32 v38, v37
	v_pk_mul_f32 v[36:37], v[38:39], v[40:41]
	v_pk_mul_f32 v[46:47], v[48:49], v[46:47]
	v_bfe_u32 v38, v37, 16, 1
	v_bfe_u32 v39, v36, 16, 1
	v_bfe_u32 v40, v33, 16, 1
	v_bfe_u32 v41, v32, 16, 1
	v_add3_u32 v32, v32, v41, s3
	v_add3_u32 v33, v33, v40, s3
	v_add3_u32 v36, v36, v39, s3
	v_add3_u32 v37, v37, v38, s3
	v_bfe_u32 v38, v46, 16, 1
	v_bfe_u32 v39, v47, 16, 1
	v_bfe_u32 v40, v34, 16, 1
	v_bfe_u32 v41, v35, 16, 1
	v_add3_u32 v35, v35, v41, s3
	v_add3_u32 v34, v34, v40, s3
	v_add3_u32 v39, v47, v39, s3
	v_add3_u32 v38, v46, v38, s3
	v_lshrrev_b32_e32 v38, 16, v38
	v_lshrrev_b32_e32 v39, 16, v39
	v_lshrrev_b32_e32 v34, 16, v34
	v_lshrrev_b32_e32 v35, 16, v35
	v_and_or_b32 v35, v37, s23, v35
	v_and_or_b32 v34, v36, s23, v34
	v_and_or_b32 v33, v33, s23, v39
	v_and_or_b32 v32, v32, s23, v38
	global_store_dwordx4 v[44:45], v[32:35], off offset:1024
	s_nop 1
	v_add_u32_e32 v32, s0, v76
	v_add_u32_e32 v33, s20, v75
	v_cndmask_b32_e64 v40, v33, v32, s[42:43]
	v_ashrrev_i32_e32 v41, 31, v40
	v_lshlrev_b64 v[40:41], 11, v[40:41]
	v_lshl_add_u64 v[40:41], s[60:61], 0, v[40:41]
	v_lshl_add_u64 v[40:41], v[40:41], 0, s[36:37]
	v_lshl_add_u64 v[40:41], v[40:41], 0, v[64:65]
	v_add_co_u32_e32 v44, vcc, s1, v40
	ds_read_b128 v[32:35], v86 offset:34816
	ds_read_b128 v[36:39], v86 offset:34832
	v_addc_co_u32_e32 v45, vcc, 0, v41, vcc
	s_waitcnt lgkmcnt(1)
	v_mov_b32_e32 v49, v34
	v_mov_b32_e32 v34, v33
	v_mov_b32_e32 v48, v32
	s_waitcnt vmcnt(11)
	v_mov_b32_e32 v40, v124
	v_mov_b32_e32 v41, v125
	v_mov_b32_e32 v42, v126
	v_mov_b32_e32 v43, v127
	v_lshlrev_b32_e32 v47, 16, v41
	v_lshlrev_b32_e32 v46, 16, v40
	v_and_b32_e32 v41, 0xffff0000, v41
	v_and_b32_e32 v40, 0xffff0000, v40
	v_pk_mul_f32 v[32:33], v[34:35], v[40:41]
	v_lshlrev_b32_e32 v35, 16, v43
	v_lshlrev_b32_e32 v34, 16, v42
	s_waitcnt lgkmcnt(0)
	v_mov_b32_e32 v40, v36
	v_mov_b32_e32 v41, v38
	v_pk_mul_f32 v[34:35], v[40:41], v[34:35]
	v_and_b32_e32 v41, 0xffff0000, v43
	v_and_b32_e32 v40, 0xffff0000, v42
	v_mov_b32_e32 v38, v37
	v_pk_mul_f32 v[36:37], v[38:39], v[40:41]
	v_pk_mul_f32 v[46:47], v[48:49], v[46:47]
	v_bfe_u32 v38, v37, 16, 1
	v_bfe_u32 v39, v36, 16, 1
	v_bfe_u32 v40, v33, 16, 1
	v_bfe_u32 v41, v32, 16, 1
	v_add3_u32 v32, v32, v41, s3
	v_add3_u32 v33, v33, v40, s3
	v_add3_u32 v36, v36, v39, s3
	v_add3_u32 v37, v37, v38, s3
	v_bfe_u32 v38, v46, 16, 1
	v_bfe_u32 v39, v47, 16, 1
	v_bfe_u32 v40, v34, 16, 1
	v_bfe_u32 v41, v35, 16, 1
	v_add3_u32 v35, v35, v41, s3
	v_add3_u32 v34, v34, v40, s3
	v_add3_u32 v39, v47, v39, s3
	v_add3_u32 v38, v46, v38, s3
	v_lshrrev_b32_e32 v38, 16, v38
	v_lshrrev_b32_e32 v39, 16, v39
	v_lshrrev_b32_e32 v34, 16, v34
	v_lshrrev_b32_e32 v35, 16, v35
	v_and_or_b32 v35, v37, s23, v35
	v_and_or_b32 v34, v36, s23, v34
	v_and_or_b32 v33, v33, s23, v39
	v_and_or_b32 v32, v32, s23, v38
	global_store_dwordx4 v[44:45], v[32:35], off offset:1024
	s_nop 1
	v_add_u32_e32 v32, s0, v78
	v_add_u32_e32 v33, s20, v77
	v_cndmask_b32_e64 v40, v33, v32, s[42:43]
	v_ashrrev_i32_e32 v41, 31, v40
	v_lshlrev_b64 v[40:41], 11, v[40:41]
	v_lshl_add_u64 v[40:41], s[60:61], 0, v[40:41]
	v_lshl_add_u64 v[40:41], v[40:41], 0, s[36:37]
	v_lshl_add_u64 v[40:41], v[40:41], 0, v[64:65]
	v_add_co_u32_e32 v44, vcc, s1, v40
	ds_read_b128 v[32:35], v87 offset:34816
	ds_read_b128 v[36:39], v87 offset:34832
	v_addc_co_u32_e32 v45, vcc, 0, v41, vcc
	s_waitcnt lgkmcnt(1)
	v_mov_b32_e32 v49, v34
	v_mov_b32_e32 v34, v33
	v_mov_b32_e32 v48, v32
	s_mul_i32 s0, s17, s54
	s_add_i32 s16, s0, s7
	s_cmpk_lt_i32 s16, 0x480
	s_waitcnt vmcnt(11)
	v_mov_b32_e32 v40, v128
	v_mov_b32_e32 v41, v129
	v_mov_b32_e32 v42, v130
	v_mov_b32_e32 v43, v131
	v_lshlrev_b32_e32 v47, 16, v41
	v_lshlrev_b32_e32 v46, 16, v40
	v_and_b32_e32 v41, 0xffff0000, v41
	v_and_b32_e32 v40, 0xffff0000, v40
	v_pk_mul_f32 v[32:33], v[34:35], v[40:41]
	v_lshlrev_b32_e32 v35, 16, v43
	v_lshlrev_b32_e32 v34, 16, v42
	s_waitcnt lgkmcnt(0)
	v_mov_b32_e32 v40, v36
	v_mov_b32_e32 v41, v38
	v_pk_mul_f32 v[34:35], v[40:41], v[34:35]
	v_and_b32_e32 v41, 0xffff0000, v43
	v_and_b32_e32 v40, 0xffff0000, v42
	v_mov_b32_e32 v38, v37
	v_pk_mul_f32 v[36:37], v[38:39], v[40:41]
	v_pk_mul_f32 v[46:47], v[48:49], v[46:47]
	v_bfe_u32 v38, v37, 16, 1
	v_bfe_u32 v39, v36, 16, 1
	v_bfe_u32 v40, v33, 16, 1
	v_bfe_u32 v41, v32, 16, 1
	v_add3_u32 v32, v32, v41, s3
	v_add3_u32 v33, v33, v40, s3
	v_add3_u32 v36, v36, v39, s3
	v_add3_u32 v37, v37, v38, s3
	v_bfe_u32 v38, v46, 16, 1
	v_bfe_u32 v39, v47, 16, 1
	v_bfe_u32 v40, v34, 16, 1
	v_bfe_u32 v41, v35, 16, 1
	v_add3_u32 v35, v35, v41, s3
	v_add3_u32 v34, v34, v40, s3
	v_add3_u32 v39, v47, v39, s3
	v_add3_u32 v38, v46, v38, s3
	v_lshrrev_b32_e32 v38, 16, v38
	v_lshrrev_b32_e32 v39, 16, v39
	v_lshrrev_b32_e32 v34, 16, v34
	v_lshrrev_b32_e32 v35, 16, v35
	v_and_or_b32 v35, v37, s23, v35
	v_and_or_b32 v34, v36, s23, v34
	v_and_or_b32 v33, v33, s23, v39
	v_and_or_b32 v32, v32, s23, v38
	global_store_dwordx4 v[44:45], v[32:35], off offset:1024
	s_cbranch_scc0 .LBB0_426

.LBB0_405:
	s_add_i32 s24, s16, s54
	v_add_u32_e32 v32, v69, v67
	s_cmpk_gt_i32 s24, 0x47f
	s_waitcnt lgkmcnt(0)
	s_barrier
	s_waitcnt vmcnt(4)
	ds_write_b128 v32, v[4:7] offset:34816
	ds_write_b128 v79, v[0:3] offset:33792
	ds_write_b128 v32, v[12:15] offset:34944
	ds_write_b128 v79, v[8:11] offset:33920
	ds_write_b128 v32, v[20:23] offset:35072
	ds_write_b128 v79, v[16:19] offset:34048
	ds_write_b128 v32, v[28:31] offset:35200
	ds_write_b128 v79, v[24:27] offset:34176
	s_waitcnt lgkmcnt(0)
	s_barrier
	s_cbranch_scc1 .LBB0_400
	s_cmpk_gt_i32 s24, 0x3ff
	s_cselect_b64 s[0:1], -1, 0
	s_mov_b64 s[18:19], -1
	s_and_b64 vcc, exec, s[0:1]
	s_cbranch_vccz .LBB0_408
	s_add_i32 s10, s24, 0xfffffc40
	s_mov_b64 s[18:19], 0
